# 8-phase K-loops (P4,P5,P6): h0 fragment reads moved from read sections 1/5 to the read-free sections 8/4 of the previous k-tile (+vmcnt(10) in sections 3/7), so the lgkmcnt(8) wait no longer exposes a
# speedup vs baseline: 1.0011x; 1.0011x over previous
.LBB0_94:
	s_lshl_b32 s70, s83, 12
	s_add_i32 m0, s43, 0x18000
	v_lshl_add_u64 v[8:9], v[8:9], 0, s[48:49]
	s_lshl_b32 s71, s74, 13
	s_and_b32 s70, s70, 0x3000
	s_waitcnt vmcnt(4)
	s_barrier
	global_load_lds_dwordx4 v[8:9], off
	v_lshl_add_u64 v[6:7], v[6:7], 0, s[48:49]
	s_add_i32 m0, s43, 0x1a000
	s_add_i32 s74, s43, 0x8000
	s_add_i32 vcc_lo, s43, 0xa000
	global_load_lds_dwordx4 v[6:7], off
	v_lshl_add_u64 v[4:5], v[4:5], 0, s[48:49]
	s_mov_b32 m0, s74
	s_add_u32 s40, s40, 0xb0080
	global_load_lds_dwordx4 v[4:5], off
	v_lshl_add_u64 v[2:3], v[2:3], 0, s[48:49]
	s_mov_b32 m0, vcc_lo
	s_addc_u32 s41, s41, 0
	global_load_lds_dwordx4 v[2:3], off
	s_add_i32 m0, s43, 0x1c000
	v_lshl_add_u64 v[2:3], s[40:41], 0, v[130:131]
	global_load_lds_dwordx4 v[2:3], off
	v_lshl_add_u64 v[2:3], s[40:41], 0, v[132:133]
	s_add_i32 m0, s43, 0x1e000
	v_and_b32_e32 v19, 15, v18
	global_load_lds_dwordx4 v[2:3], off
	v_and_b32_e32 v20, 48, v18
	v_lshlrev_b32_e32 v18, 2, v18
	v_lshlrev_b32_e32 v19, 6, v19
	v_and_b32_e32 v18, 32, v18
	v_or_b32_e32 v21, v19, v20
	v_bitop3_b32 v19, v19, v18, v20 bitop3:0x36
	v_or_b32_e32 v143, s70, v19
	s_movk_i32 s70, 0xb00
	v_bitop3_b32 v18, v21, s71, v18 bitop3:0xde
	v_lshrrev_b32_e32 v3, 1, v10
	v_mul_lo_u32 v2, v12, s70
	s_mov_b32 s71, 0xb000
	v_mad_u64_u32 v[2:3], s[40:41], v3, s71, v[2:3]
	v_readlane_b32 s18, v253, 1
	v_readlane_b32 s19, v253, 2
	s_add_u32 s40, s18, s76
	s_addc_u32 s41, s19, s75
	v_lshrrev_b32_e32 v5, 1, v13
	v_mul_lo_u32 v4, v16, s70
	v_or_b32_e32 v2, v2, v11
	v_mad_u64_u32 v[4:5], s[70:71], v5, s71, v[4:5]
	s_add_u32 s36, s18, s36
	s_waitcnt vmcnt(6)
	v_add_lshl_u32 v2, v2, v14, 1
	v_mov_b32_e32 v3, v196
	v_or_b32_e32 v4, v4, v15
	s_addc_u32 s37, s19, s37
	v_lshl_add_u64 v[134:135], s[40:41], 0, v[2:3]
	v_add_lshl_u32 v4, v4, v17, 1
	v_mov_b32_e32 v5, v196
	v_lshl_add_u64 v[138:139], s[36:37], 0, v[2:3]
	v_mov_b32_e32 v2, 0
	v_lshl_add_u64 v[136:137], s[40:41], 0, v[4:5]
	v_lshl_add_u64 v[140:141], s[36:37], 0, v[4:5]
	s_mov_b32 s36, -2
	v_add_u32_e32 v142, 0, v18
	v_mov_b32_e32 v3, v2
	v_mov_b32_e32 v4, v2
	v_mov_b32_e32 v5, v2
	v_mov_b32_e32 v6, v2
	v_mov_b32_e32 v7, v2
	v_mov_b32_e32 v8, v2
	v_mov_b32_e32 v9, v2
	v_mov_b32_e32 v10, v2
	v_mov_b32_e32 v11, v2
	v_mov_b32_e32 v12, v2
	v_mov_b32_e32 v13, v2
	v_mov_b32_e32 v14, v2
	v_mov_b32_e32 v15, v2
	v_mov_b32_e32 v16, v2
	v_mov_b32_e32 v17, v2
	v_mov_b32_e32 v18, v2
	v_mov_b32_e32 v19, v2
	v_mov_b32_e32 v20, v2
	v_mov_b32_e32 v21, v2
	v_mov_b32_e32 v22, v2
	v_mov_b32_e32 v23, v2
	v_mov_b32_e32 v24, v2
	v_mov_b32_e32 v25, v2
	v_mov_b32_e32 v26, v2
	v_mov_b32_e32 v27, v2
	v_mov_b32_e32 v28, v2
	v_mov_b32_e32 v29, v2
	v_mov_b32_e32 v30, v2
	v_mov_b32_e32 v31, v2
	v_mov_b32_e32 v32, v2
	v_mov_b32_e32 v33, v2
	v_mov_b32_e32 v34, v2
	v_mov_b32_e32 v35, v2
	v_mov_b32_e32 v36, v2
	v_mov_b32_e32 v37, v2
	v_mov_b32_e32 v38, v2
	v_mov_b32_e32 v39, v2
	v_mov_b32_e32 v40, v2
	v_mov_b32_e32 v41, v2
	v_mov_b32_e32 v42, v2
	v_mov_b32_e32 v43, v2
	v_mov_b32_e32 v44, v2
	v_mov_b32_e32 v45, v2
	v_mov_b32_e32 v46, v2
	v_mov_b32_e32 v47, v2
	v_mov_b32_e32 v48, v2
	v_mov_b32_e32 v49, v2
	v_mov_b32_e32 v50, v2
	v_mov_b32_e32 v51, v2
	v_mov_b32_e32 v52, v2
	v_mov_b32_e32 v53, v2
	v_mov_b32_e32 v54, v2
	v_mov_b32_e32 v55, v2
	v_mov_b32_e32 v56, v2
	v_mov_b32_e32 v57, v2
	v_mov_b32_e32 v58, v2
	v_mov_b32_e32 v59, v2
	v_mov_b32_e32 v60, v2
	v_mov_b32_e32 v61, v2
	v_mov_b32_e32 v62, v2
	v_mov_b32_e32 v63, v2
	v_mov_b32_e32 v64, v2
	v_mov_b32_e32 v65, v2
	v_mov_b32_e32 v66, v2
	v_mov_b32_e32 v67, v2
	v_mov_b32_e32 v68, v2
	v_mov_b32_e32 v69, v2
	v_mov_b32_e32 v70, v2
	v_mov_b32_e32 v71, v2
	v_mov_b32_e32 v72, v2
	v_mov_b32_e32 v73, v2
	v_mov_b32_e32 v78, v2
	v_mov_b32_e32 v79, v2
	v_mov_b32_e32 v80, v2
	v_mov_b32_e32 v81, v2
	v_mov_b32_e32 v82, v2
	v_mov_b32_e32 v83, v2
	v_mov_b32_e32 v84, v2
	v_mov_b32_e32 v85, v2
	v_mov_b32_e32 v86, v2
	v_mov_b32_e32 v87, v2
	v_mov_b32_e32 v88, v2
	v_mov_b32_e32 v89, v2
	v_mov_b32_e32 v90, v2
	v_mov_b32_e32 v91, v2
	v_mov_b32_e32 v92, v2
	v_mov_b32_e32 v93, v2
	v_mov_b32_e32 v94, v2
	v_mov_b32_e32 v95, v2
	v_mov_b32_e32 v96, v2
	v_mov_b32_e32 v97, v2
	v_mov_b32_e32 v98, v2
	v_mov_b32_e32 v99, v2
	v_mov_b32_e32 v100, v2
	v_mov_b32_e32 v101, v2
	v_mov_b32_e32 v102, v2
	v_mov_b32_e32 v103, v2
	v_mov_b32_e32 v104, v2
	v_mov_b32_e32 v105, v2
	v_mov_b32_e32 v106, v2
	v_mov_b32_e32 v107, v2
	v_mov_b32_e32 v108, v2
	v_mov_b32_e32 v109, v2
	v_mov_b32_e32 v110, v2
	v_mov_b32_e32 v111, v2
	v_mov_b32_e32 v112, v2
	v_mov_b32_e32 v113, v2
	v_mov_b32_e32 v114, v2
	v_mov_b32_e32 v115, v2
	v_mov_b32_e32 v116, v2
	v_mov_b32_e32 v117, v2
	v_mov_b32_e32 v118, v2
	v_mov_b32_e32 v119, v2
	v_mov_b32_e32 v120, v2
	v_mov_b32_e32 v121, v2
	v_mov_b32_e32 v122, v2
	v_mov_b32_e32 v123, v2
	v_mov_b32_e32 v124, v2
	v_mov_b32_e32 v125, v2
	v_mov_b32_e32 v126, v2
	v_mov_b32_e32 v127, v2
	v_mov_b32_e32 v128, v2
	v_mov_b32_e32 v129, v2
	v_mov_b32_e32 v74, v2
	v_mov_b32_e32 v75, v2
	v_mov_b32_e32 v76, v2
	v_mov_b32_e32 v77, v2
	s_mov_b64 s[44:45], 0x4030080
	s_mov_b64 s[76:77], 0x1a00100
	s_mov_b64 s[82:83], 0x3f80100
	s_mov_b64 s[80:81], 0x1ab0100
	s_mov_b64 s[18:19], 0x4030100
	s_mov_b64 s[52:53], 0x1a00180
	s_mov_b64 s[54:55], 0x3f80180
	s_mov_b64 s[56:57], 0x1ab0180
	s_barrier
	v_add_u32_e32 v156, 0x10000, v143
	ds_read_b128 v[144:147], v156
	ds_read_b128 v[148:151], v156 offset:1024
	ds_read_b128 v[152:155], v156 offset:2048
	ds_read_b128 v[156:159], v156 offset:3072
.LBB0_95:
	s_add_i32 s41, 0, 0x10000
	v_lshl_add_u64 v[210:211], v[138:139], 0, s[14:15]
	s_add_i32 s40, s43, 0xc000
	v_lshl_add_u64 v[192:193], v[210:211], 0, s[44:45]
	s_mov_b32 m0, s40
	v_lshl_add_u64 v[212:213], v[140:141], 0, s[14:15]
	s_add_i32 s37, s43, 0xe000
	ds_read_b128 v[160:163], v142
	ds_read_b128 v[164:167], v142 offset:1024
	ds_read_b128 v[168:171], v142 offset:2048
	ds_read_b128 v[172:175], v142 offset:3072
	ds_read_b128 v[176:179], v142 offset:4096
	ds_read_b128 v[180:183], v142 offset:5120
	ds_read_b128 v[184:187], v142 offset:6144
	ds_read_b128 v[188:191], v142 offset:7168
	global_load_lds_dwordx4 v[192:193], off
	v_lshl_add_u64 v[192:193], v[212:213], 0, s[44:45]
	s_mov_b32 m0, s37
	s_nop 0
	global_load_lds_dwordx4 v[192:193], off
	s_waitcnt lgkmcnt(8)
	s_barrier
	s_waitcnt lgkmcnt(0)
	s_setprio 1
	s_waitcnt lgkmcnt(0)
	v_mfma_f32_16x16x32_bf16 v[126:129], v[144:147], v[160:163], v[126:129]
	v_mfma_f32_16x16x32_bf16 v[122:125], v[152:155], v[160:163], v[122:125]
	v_mfma_f32_16x16x32_bf16 v[118:121], v[144:147], v[168:171], v[118:121]
	v_mfma_f32_16x16x32_bf16 v[114:117], v[152:155], v[168:171], v[114:117]
	v_mfma_f32_16x16x32_bf16 v[110:113], v[144:147], v[176:179], v[110:113]
	v_mfma_f32_16x16x32_bf16 v[106:109], v[152:155], v[176:179], v[106:109]
	v_mfma_f32_16x16x32_bf16 v[102:105], v[144:147], v[184:187], v[102:105]
	v_mfma_f32_16x16x32_bf16 v[98:101], v[152:155], v[184:187], v[98:101]
	v_mfma_f32_16x16x32_bf16 v[126:129], v[148:151], v[164:167], v[126:129]
	v_mfma_f32_16x16x32_bf16 v[122:125], v[156:159], v[164:167], v[122:125]
	v_mfma_f32_16x16x32_bf16 v[118:121], v[148:151], v[172:175], v[118:121]
	v_mfma_f32_16x16x32_bf16 v[114:117], v[156:159], v[172:175], v[114:117]
	v_mfma_f32_16x16x32_bf16 v[110:113], v[148:151], v[180:183], v[110:113]
	v_mfma_f32_16x16x32_bf16 v[106:109], v[156:159], v[180:183], v[106:109]
	v_mfma_f32_16x16x32_bf16 v[102:105], v[148:151], v[188:191], v[102:105]
	v_mfma_f32_16x16x32_bf16 v[98:101], v[156:159], v[188:191], v[98:101]
	s_setprio 0
	s_barrier
	s_add_i32 s70, 0, 0x14000
	v_lshl_add_u64 v[214:215], v[134:135], 0, s[14:15]
	s_add_i32 s41, s41, s42
	v_add_u32_e32 v197, s70, v143
	v_lshl_add_u64 v[216:217], v[214:215], 0, s[76:77]
	s_mov_b32 m0, s41
	ds_read_b128 v[192:195], v197
	ds_read_b128 v[198:201], v197 offset:1024
	ds_read_b128 v[202:205], v197 offset:2048
	ds_read_b128 v[206:209], v197 offset:3072
	global_load_lds_dwordx4 v[216:217], off
	v_lshl_add_u64 v[216:217], v[136:137], 0, s[14:15]
	v_lshl_add_u64 v[218:219], v[216:217], 0, s[76:77]
	s_add_i32 m0, s41, 0x2000
	s_nop 0
	global_load_lds_dwordx4 v[218:219], off
	s_barrier
	s_waitcnt lgkmcnt(0)
	s_setprio 1
	s_waitcnt lgkmcnt(0)
	v_mfma_f32_16x16x32_bf16 v[94:97], v[192:195], v[160:163], v[94:97]
	v_mfma_f32_16x16x32_bf16 v[90:93], v[202:205], v[160:163], v[90:93]
	v_mfma_f32_16x16x32_bf16 v[86:89], v[192:195], v[168:171], v[86:89]
	v_mfma_f32_16x16x32_bf16 v[82:85], v[202:205], v[168:171], v[82:85]
	v_mfma_f32_16x16x32_bf16 v[78:81], v[192:195], v[176:179], v[78:81]
	v_mfma_f32_16x16x32_bf16 v[70:73], v[202:205], v[176:179], v[70:73]
	v_mfma_f32_16x16x32_bf16 v[66:69], v[192:195], v[184:187], v[66:69]
	v_mfma_f32_16x16x32_bf16 v[62:65], v[202:205], v[184:187], v[62:65]
	v_mfma_f32_16x16x32_bf16 v[94:97], v[198:201], v[164:167], v[94:97]
	v_mfma_f32_16x16x32_bf16 v[90:93], v[206:209], v[164:167], v[90:93]
	v_mfma_f32_16x16x32_bf16 v[86:89], v[198:201], v[172:175], v[86:89]
	v_mfma_f32_16x16x32_bf16 v[82:85], v[206:209], v[172:175], v[82:85]
	v_mfma_f32_16x16x32_bf16 v[78:81], v[198:201], v[180:183], v[78:81]
	v_mfma_f32_16x16x32_bf16 v[70:73], v[206:209], v[180:183], v[70:73]
	v_mfma_f32_16x16x32_bf16 v[66:69], v[198:201], v[188:191], v[66:69]
	v_mfma_f32_16x16x32_bf16 v[62:65], v[206:209], v[188:191], v[62:65]
	s_setprio 0
	s_mov_b32 m0, s43
	v_lshl_add_u64 v[218:219], v[210:211], 0, s[82:83]
	s_barrier
	ds_read_b128 v[160:163], v142 offset:16384
	ds_read_b128 v[164:167], v142 offset:17408
	ds_read_b128 v[168:171], v142 offset:18432
	ds_read_b128 v[172:175], v142 offset:19456
	ds_read_b128 v[176:179], v142 offset:20480
	ds_read_b128 v[180:183], v142 offset:21504
	ds_read_b128 v[184:187], v142 offset:22528
	ds_read_b128 v[188:191], v142 offset:23552
	global_load_lds_dwordx4 v[218:219], off
	v_lshl_add_u64 v[218:219], v[212:213], 0, s[82:83]
	s_mov_b32 m0, s73
	s_nop 0
	global_load_lds_dwordx4 v[218:219], off
	s_waitcnt vmcnt(10)
	s_barrier
	s_waitcnt lgkmcnt(0)
	s_setprio 1
	s_waitcnt lgkmcnt(0)
	v_mfma_f32_16x16x32_bf16 v[58:61], v[144:147], v[160:163], v[58:61]
	v_mfma_f32_16x16x32_bf16 v[54:57], v[152:155], v[160:163], v[54:57]
	v_mfma_f32_16x16x32_bf16 v[50:53], v[144:147], v[168:171], v[50:53]
	v_mfma_f32_16x16x32_bf16 v[46:49], v[152:155], v[168:171], v[46:49]
	v_mfma_f32_16x16x32_bf16 v[42:45], v[144:147], v[176:179], v[42:45]
	v_mfma_f32_16x16x32_bf16 v[38:41], v[152:155], v[176:179], v[38:41]
	v_mfma_f32_16x16x32_bf16 v[34:37], v[144:147], v[184:187], v[34:37]
	v_mfma_f32_16x16x32_bf16 v[30:33], v[152:155], v[184:187], v[30:33]
	v_mfma_f32_16x16x32_bf16 v[58:61], v[148:151], v[164:167], v[58:61]
	v_mfma_f32_16x16x32_bf16 v[54:57], v[156:159], v[164:167], v[54:57]
	v_mfma_f32_16x16x32_bf16 v[50:53], v[148:151], v[172:175], v[50:53]
	v_mfma_f32_16x16x32_bf16 v[46:49], v[156:159], v[172:175], v[46:49]
	v_mfma_f32_16x16x32_bf16 v[42:45], v[148:151], v[180:183], v[42:45]
	v_mfma_f32_16x16x32_bf16 v[38:41], v[156:159], v[180:183], v[38:41]
	v_mfma_f32_16x16x32_bf16 v[34:37], v[148:151], v[188:191], v[34:37]
	v_mfma_f32_16x16x32_bf16 v[30:33], v[156:159], v[188:191], v[30:33]
	s_setprio 0
	s_barrier
	s_add_i32 s41, s70, s42
	v_lshl_add_u64 v[144:145], v[214:215], 0, s[80:81]
	s_mov_b32 m0, s41
	s_nop 0
	global_load_lds_dwordx4 v[144:145], off
	v_lshl_add_u64 v[144:145], v[216:217], 0, s[80:81]
	s_add_i32 m0, s41, 0x2000
	s_nop 0
	global_load_lds_dwordx4 v[144:145], off
	v_add_u32_e32 v156, 0x18000, v143
	ds_read_b128 v[144:147], v156
	ds_read_b128 v[148:151], v156 offset:1024
	ds_read_b128 v[152:155], v156 offset:2048
	ds_read_b128 v[156:159], v156 offset:3072
	s_waitcnt vmcnt(6)
	s_barrier
	s_setprio 1
	v_mfma_f32_16x16x32_bf16 v[26:29], v[192:195], v[160:163], v[26:29]
	v_mfma_f32_16x16x32_bf16 v[22:25], v[202:205], v[160:163], v[22:25]
	v_mfma_f32_16x16x32_bf16 v[18:21], v[192:195], v[168:171], v[18:21]
	v_mfma_f32_16x16x32_bf16 v[14:17], v[202:205], v[168:171], v[14:17]
	v_mfma_f32_16x16x32_bf16 v[10:13], v[192:195], v[176:179], v[10:13]
	v_mfma_f32_16x16x32_bf16 v[6:9], v[202:205], v[176:179], v[6:9]
	v_mfma_f32_16x16x32_bf16 v[2:5], v[192:195], v[184:187], v[2:5]
	v_mfma_f32_16x16x32_bf16 v[74:77], v[202:205], v[184:187], v[74:77]
	v_mfma_f32_16x16x32_bf16 v[26:29], v[198:201], v[164:167], v[26:29]
	v_mfma_f32_16x16x32_bf16 v[22:25], v[206:209], v[164:167], v[22:25]
	v_mfma_f32_16x16x32_bf16 v[18:21], v[198:201], v[172:175], v[18:21]
	v_mfma_f32_16x16x32_bf16 v[14:17], v[206:209], v[172:175], v[14:17]
	v_mfma_f32_16x16x32_bf16 v[10:13], v[198:201], v[180:183], v[10:13]
	v_mfma_f32_16x16x32_bf16 v[6:9], v[206:209], v[180:183], v[6:9]
	v_mfma_f32_16x16x32_bf16 v[2:5], v[198:201], v[188:191], v[2:5]
	v_mfma_f32_16x16x32_bf16 v[74:77], v[206:209], v[188:191], v[74:77]
	s_setprio 0
	s_add_i32 s41, 0, 0x18000
	s_barrier
	s_mov_b32 m0, s78
	v_lshl_add_u64 v[192:193], v[210:211], 0, s[18:19]
	ds_read_b128 v[160:163], v142 offset:32768
	ds_read_b128 v[164:167], v142 offset:33792
	ds_read_b128 v[168:171], v142 offset:34816
	ds_read_b128 v[172:175], v142 offset:35840
	ds_read_b128 v[176:179], v142 offset:36864
	ds_read_b128 v[180:183], v142 offset:37888
	ds_read_b128 v[184:187], v142 offset:38912
	ds_read_b128 v[188:191], v142 offset:39936
	global_load_lds_dwordx4 v[192:193], off
	v_lshl_add_u64 v[192:193], v[212:213], 0, s[18:19]
	s_mov_b32 m0, s79
	s_nop 0
	global_load_lds_dwordx4 v[192:193], off
	s_waitcnt lgkmcnt(8)
	s_barrier
	s_waitcnt lgkmcnt(0)
	s_setprio 1
	s_waitcnt lgkmcnt(0)
	v_mfma_f32_16x16x32_bf16 v[126:129], v[144:147], v[160:163], v[126:129]
	v_mfma_f32_16x16x32_bf16 v[122:125], v[152:155], v[160:163], v[122:125]
	v_mfma_f32_16x16x32_bf16 v[118:121], v[144:147], v[168:171], v[118:121]
	v_mfma_f32_16x16x32_bf16 v[114:117], v[152:155], v[168:171], v[114:117]
	v_mfma_f32_16x16x32_bf16 v[110:113], v[144:147], v[176:179], v[110:113]
	v_mfma_f32_16x16x32_bf16 v[106:109], v[152:155], v[176:179], v[106:109]
	v_mfma_f32_16x16x32_bf16 v[102:105], v[144:147], v[184:187], v[102:105]
	v_mfma_f32_16x16x32_bf16 v[98:101], v[152:155], v[184:187], v[98:101]
	v_mfma_f32_16x16x32_bf16 v[126:129], v[148:151], v[164:167], v[126:129]
	v_mfma_f32_16x16x32_bf16 v[122:125], v[156:159], v[164:167], v[122:125]
	v_mfma_f32_16x16x32_bf16 v[118:121], v[148:151], v[172:175], v[118:121]
	v_mfma_f32_16x16x32_bf16 v[114:117], v[156:159], v[172:175], v[114:117]
	v_mfma_f32_16x16x32_bf16 v[110:113], v[148:151], v[180:183], v[110:113]
	v_mfma_f32_16x16x32_bf16 v[106:109], v[156:159], v[180:183], v[106:109]
	v_mfma_f32_16x16x32_bf16 v[102:105], v[148:151], v[188:191], v[102:105]
	v_mfma_f32_16x16x32_bf16 v[98:101], v[156:159], v[188:191], v[98:101]
	s_setprio 0
	s_barrier
	s_add_i32 s70, 0, 0x1c000
	s_add_i32 s41, s41, s42
	v_add_u32_e32 v197, s70, v143
	v_lshl_add_u64 v[218:219], v[214:215], 0, s[52:53]
	s_mov_b32 m0, s41
	ds_read_b128 v[192:195], v197
	ds_read_b128 v[198:201], v197 offset:1024
	ds_read_b128 v[202:205], v197 offset:2048
	ds_read_b128 v[206:209], v197 offset:3072
	global_load_lds_dwordx4 v[218:219], off
	v_lshl_add_u64 v[218:219], v[216:217], 0, s[52:53]
	s_add_i32 m0, s41, 0x2000
	s_nop 0
	global_load_lds_dwordx4 v[218:219], off
	s_barrier
	s_waitcnt lgkmcnt(0)
	s_setprio 1
	s_waitcnt lgkmcnt(0)
	v_mfma_f32_16x16x32_bf16 v[94:97], v[192:195], v[160:163], v[94:97]
	v_mfma_f32_16x16x32_bf16 v[90:93], v[202:205], v[160:163], v[90:93]
	v_mfma_f32_16x16x32_bf16 v[86:89], v[192:195], v[168:171], v[86:89]
	v_mfma_f32_16x16x32_bf16 v[82:85], v[202:205], v[168:171], v[82:85]
	v_mfma_f32_16x16x32_bf16 v[78:81], v[192:195], v[176:179], v[78:81]
	v_mfma_f32_16x16x32_bf16 v[70:73], v[202:205], v[176:179], v[70:73]
	v_mfma_f32_16x16x32_bf16 v[66:69], v[192:195], v[184:187], v[66:69]
	v_mfma_f32_16x16x32_bf16 v[62:65], v[202:205], v[184:187], v[62:65]
	v_mfma_f32_16x16x32_bf16 v[94:97], v[198:201], v[164:167], v[94:97]
	v_mfma_f32_16x16x32_bf16 v[90:93], v[206:209], v[164:167], v[90:93]
	v_mfma_f32_16x16x32_bf16 v[86:89], v[198:201], v[172:175], v[86:89]
	v_mfma_f32_16x16x32_bf16 v[82:85], v[206:209], v[172:175], v[82:85]
	v_mfma_f32_16x16x32_bf16 v[78:81], v[198:201], v[180:183], v[78:81]
	v_mfma_f32_16x16x32_bf16 v[70:73], v[206:209], v[180:183], v[70:73]
	v_mfma_f32_16x16x32_bf16 v[66:69], v[198:201], v[188:191], v[66:69]
	v_mfma_f32_16x16x32_bf16 v[62:65], v[206:209], v[188:191], v[62:65]
	s_setprio 0
	s_mov_b32 m0, s74
	v_lshl_add_u64 v[210:211], v[210:211], 0, s[54:55]
	s_barrier
	ds_read_b128 v[160:163], v142 offset:49152
	ds_read_b128 v[164:167], v142 offset:50176
	ds_read_b128 v[168:171], v142 offset:51200
	ds_read_b128 v[172:175], v142 offset:52224
	ds_read_b128 v[176:179], v142 offset:53248
	ds_read_b128 v[180:183], v142 offset:54272
	ds_read_b128 v[184:187], v142 offset:55296
	ds_read_b128 v[188:191], v142 offset:56320
	global_load_lds_dwordx4 v[210:211], off
	v_lshl_add_u64 v[210:211], v[212:213], 0, s[54:55]
	s_mov_b32 m0, vcc_lo
	s_nop 0
	global_load_lds_dwordx4 v[210:211], off
	s_waitcnt vmcnt(10)
	s_barrier
	s_waitcnt lgkmcnt(0)
	s_setprio 1
	s_waitcnt lgkmcnt(0)
	v_mfma_f32_16x16x32_bf16 v[58:61], v[144:147], v[160:163], v[58:61]
	v_mfma_f32_16x16x32_bf16 v[54:57], v[152:155], v[160:163], v[54:57]
	v_mfma_f32_16x16x32_bf16 v[50:53], v[144:147], v[168:171], v[50:53]
	v_mfma_f32_16x16x32_bf16 v[46:49], v[152:155], v[168:171], v[46:49]
	v_mfma_f32_16x16x32_bf16 v[42:45], v[144:147], v[176:179], v[42:45]
	v_mfma_f32_16x16x32_bf16 v[38:41], v[152:155], v[176:179], v[38:41]
	v_mfma_f32_16x16x32_bf16 v[34:37], v[144:147], v[184:187], v[34:37]
	v_mfma_f32_16x16x32_bf16 v[30:33], v[152:155], v[184:187], v[30:33]
	v_mfma_f32_16x16x32_bf16 v[58:61], v[148:151], v[164:167], v[58:61]
	v_mfma_f32_16x16x32_bf16 v[54:57], v[156:159], v[164:167], v[54:57]
	v_mfma_f32_16x16x32_bf16 v[50:53], v[148:151], v[172:175], v[50:53]
	v_mfma_f32_16x16x32_bf16 v[46:49], v[156:159], v[172:175], v[46:49]
	v_mfma_f32_16x16x32_bf16 v[42:45], v[148:151], v[180:183], v[42:45]
	v_mfma_f32_16x16x32_bf16 v[38:41], v[156:159], v[180:183], v[38:41]
	v_mfma_f32_16x16x32_bf16 v[34:37], v[148:151], v[188:191], v[34:37]
	v_mfma_f32_16x16x32_bf16 v[30:33], v[156:159], v[188:191], v[30:33]
	s_setprio 0
	s_barrier
	s_add_i32 s41, s70, s42
	v_lshl_add_u64 v[144:145], v[214:215], 0, s[56:57]
	s_mov_b32 m0, s41
	s_nop 0
	global_load_lds_dwordx4 v[144:145], off
	v_lshl_add_u64 v[144:145], v[216:217], 0, s[56:57]
	s_add_i32 m0, s41, 0x2000
	s_nop 0
	global_load_lds_dwordx4 v[144:145], off
	v_add_u32_e32 v156, 0x10000, v143
	ds_read_b128 v[144:147], v156
	ds_read_b128 v[148:151], v156 offset:1024
	ds_read_b128 v[152:155], v156 offset:2048
	ds_read_b128 v[156:159], v156 offset:3072
	s_waitcnt vmcnt(6)
	s_barrier
	s_setprio 1
	v_mfma_f32_16x16x32_bf16 v[26:29], v[192:195], v[160:163], v[26:29]
	v_mfma_f32_16x16x32_bf16 v[22:25], v[202:205], v[160:163], v[22:25]
	v_mfma_f32_16x16x32_bf16 v[18:21], v[192:195], v[168:171], v[18:21]
	v_mfma_f32_16x16x32_bf16 v[14:17], v[202:205], v[168:171], v[14:17]
	v_mfma_f32_16x16x32_bf16 v[10:13], v[192:195], v[176:179], v[10:13]
	v_mfma_f32_16x16x32_bf16 v[6:9], v[202:205], v[176:179], v[6:9]
	v_mfma_f32_16x16x32_bf16 v[2:5], v[192:195], v[184:187], v[2:5]
	v_mfma_f32_16x16x32_bf16 v[74:77], v[202:205], v[184:187], v[74:77]
	v_mfma_f32_16x16x32_bf16 v[26:29], v[198:201], v[164:167], v[26:29]
	v_mfma_f32_16x16x32_bf16 v[22:25], v[206:209], v[164:167], v[22:25]
	v_mfma_f32_16x16x32_bf16 v[18:21], v[198:201], v[172:175], v[18:21]
	v_mfma_f32_16x16x32_bf16 v[14:17], v[206:209], v[172:175], v[14:17]
	v_mfma_f32_16x16x32_bf16 v[10:13], v[198:201], v[180:183], v[10:13]
	v_mfma_f32_16x16x32_bf16 v[6:9], v[206:209], v[180:183], v[6:9]
	v_mfma_f32_16x16x32_bf16 v[2:5], v[198:201], v[188:191], v[2:5]
	v_mfma_f32_16x16x32_bf16 v[74:77], v[206:209], v[188:191], v[74:77]
	s_setprio 0
	s_add_i32 s36, s36, 2
	v_lshl_add_u64 v[134:135], v[134:135], 0, s[98:99]
	v_lshl_add_u64 v[136:137], v[136:137], 0, s[98:99]
	v_lshl_add_u64 v[138:139], v[138:139], 0, s[98:99]
	s_cmp_gt_u32 s36, 39
	v_lshl_add_u64 v[140:141], v[140:141], 0, s[98:99]
	s_barrier
	s_cbranch_scc0 .LBB0_95
	s_waitcnt lgkmcnt(0)
	s_add_u32 s16, s16, 0xb1580
	v_add_u32_e32 v143, 0, v143
	s_addc_u32 s17, s17, 0
	s_mov_b32 m0, s40
	v_add_u32_e32 v148, 0x10000, v143
	v_lshl_add_u64 v[130:131], s[16:17], 0, v[130:131]
	ds_read_b128 v[134:137], v148
	ds_read_b128 v[138:141], v148 offset:1024
	ds_read_b128 v[144:147], v148 offset:2048
	ds_read_b128 v[148:151], v148 offset:3072
	ds_read_b128 v[152:155], v142
	ds_read_b128 v[156:159], v142 offset:1024
	ds_read_b128 v[160:163], v142 offset:2048
	ds_read_b128 v[164:167], v142 offset:3072
	ds_read_b128 v[168:171], v142 offset:4096
	ds_read_b128 v[172:175], v142 offset:5120
	ds_read_b128 v[176:179], v142 offset:6144
	ds_read_b128 v[180:183], v142 offset:7168
	global_load_lds_dwordx4 v[130:131], off
	v_lshl_add_u64 v[130:131], s[16:17], 0, v[132:133]
	s_mov_b32 m0, s37
	s_nop 0
	global_load_lds_dwordx4 v[130:131], off
	s_barrier
	s_waitcnt lgkmcnt(0)
	s_setprio 1
	s_waitcnt lgkmcnt(0)
	v_mfma_f32_16x16x32_bf16 v[126:129], v[134:137], v[152:155], v[126:129]
	v_mfma_f32_16x16x32_bf16 v[122:125], v[144:147], v[152:155], v[122:125]
	v_mfma_f32_16x16x32_bf16 v[118:121], v[134:137], v[160:163], v[118:121]
	v_mfma_f32_16x16x32_bf16 v[114:117], v[144:147], v[160:163], v[114:117]
	v_mfma_f32_16x16x32_bf16 v[102:105], v[134:137], v[176:179], v[102:105]
	v_mfma_f32_16x16x32_bf16 v[126:129], v[138:141], v[156:159], v[126:129]
	v_mfma_f32_16x16x32_bf16 v[122:125], v[148:151], v[156:159], v[122:125]
	v_mfma_f32_16x16x32_bf16 v[118:121], v[138:141], v[164:167], v[118:121]
	v_mfma_f32_16x16x32_bf16 v[114:117], v[148:151], v[164:167], v[114:117]
	v_mfma_f32_16x16x32_bf16 v[110:113], v[134:137], v[168:171], v[110:113]
	v_mfma_f32_16x16x32_bf16 v[106:109], v[144:147], v[168:171], v[106:109]
	v_mfma_f32_16x16x32_bf16 v[102:105], v[138:141], v[180:183], v[102:105]
	v_mfma_f32_16x16x32_bf16 v[98:101], v[144:147], v[176:179], v[98:101]
	v_mfma_f32_16x16x32_bf16 v[110:113], v[138:141], v[172:175], v[110:113]
	v_mfma_f32_16x16x32_bf16 v[106:109], v[148:151], v[172:175], v[106:109]
	v_mfma_f32_16x16x32_bf16 v[130:133], v[148:151], v[180:183], v[98:101]
	s_setprio 0
	v_add_u32_e32 v192, 0x14000, v143
	s_barrier
	s_nop 1
	ds_read_b128 v[98:101], v192
	ds_read_b128 v[184:187], v192 offset:1024
	ds_read_b128 v[188:191], v192 offset:2048
	ds_read_b128 v[192:195], v192 offset:3072
	s_barrier
	s_waitcnt lgkmcnt(0)
	s_setprio 1
	s_waitcnt lgkmcnt(0)
	v_mfma_f32_16x16x32_bf16 v[94:97], v[98:101], v[152:155], v[94:97]
	v_mfma_f32_16x16x32_bf16 v[82:85], v[188:191], v[160:163], v[82:85]
	v_mfma_f32_16x16x32_bf16 v[62:65], v[188:191], v[176:179], v[62:65]
	v_mfma_f32_16x16x32_bf16 v[94:97], v[184:187], v[156:159], v[94:97]
	v_mfma_f32_16x16x32_bf16 v[90:93], v[188:191], v[152:155], v[90:93]
	v_mfma_f32_16x16x32_bf16 v[86:89], v[98:101], v[160:163], v[86:89]
	v_mfma_f32_16x16x32_bf16 v[82:85], v[192:195], v[164:167], v[82:85]
	v_mfma_f32_16x16x32_bf16 v[78:81], v[98:101], v[168:171], v[78:81]
	v_mfma_f32_16x16x32_bf16 v[70:73], v[188:191], v[168:171], v[70:73]
	v_mfma_f32_16x16x32_bf16 v[66:69], v[98:101], v[176:179], v[66:69]
	v_mfma_f32_16x16x32_bf16 v[62:65], v[192:195], v[180:183], v[62:65]
	v_mfma_f32_16x16x32_bf16 v[198:201], v[192:195], v[156:159], v[90:93]
	v_mfma_f32_16x16x32_bf16 v[86:89], v[184:187], v[164:167], v[86:89]
	v_mfma_f32_16x16x32_bf16 v[164:167], v[184:187], v[172:175], v[78:81]
	v_mfma_f32_16x16x32_bf16 v[168:171], v[192:195], v[172:175], v[70:73]
	v_mfma_f32_16x16x32_bf16 v[66:69], v[184:187], v[180:183], v[66:69]
	s_setprio 0
	s_barrier
	ds_read_b128 v[70:73], v142 offset:16384
	ds_read_b128 v[78:81], v142 offset:17408
	ds_read_b128 v[90:93], v142 offset:18432
	ds_read_b128 v[152:155], v142 offset:19456
	ds_read_b128 v[156:159], v142 offset:20480
	ds_read_b128 v[160:163], v142 offset:21504
	ds_read_b128 v[172:175], v142 offset:22528
	ds_read_b128 v[176:179], v142 offset:23552
	s_waitcnt vmcnt(4)
	s_barrier
	s_waitcnt lgkmcnt(0)
	s_setprio 1
	s_waitcnt lgkmcnt(0)
	v_mfma_f32_16x16x32_bf16 v[58:61], v[134:137], v[70:73], v[58:61]
	v_mfma_f32_16x16x32_bf16 v[54:57], v[144:147], v[70:73], v[54:57]
	v_mfma_f32_16x16x32_bf16 v[50:53], v[134:137], v[90:93], v[50:53]
	v_mfma_f32_16x16x32_bf16 v[42:45], v[134:137], v[156:159], v[42:45]
	v_mfma_f32_16x16x32_bf16 v[34:37], v[134:137], v[172:175], v[34:37]
	v_mfma_f32_16x16x32_bf16 v[58:61], v[138:141], v[78:81], v[58:61]
	v_mfma_f32_16x16x32_bf16 v[54:57], v[148:151], v[78:81], v[54:57]
	v_mfma_f32_16x16x32_bf16 v[50:53], v[138:141], v[152:155], v[50:53]
	v_mfma_f32_16x16x32_bf16 v[46:49], v[144:147], v[90:93], v[46:49]
	v_mfma_f32_16x16x32_bf16 v[42:45], v[138:141], v[160:163], v[42:45]
	v_mfma_f32_16x16x32_bf16 v[38:41], v[144:147], v[156:159], v[38:41]
	v_mfma_f32_16x16x32_bf16 v[34:37], v[138:141], v[176:179], v[34:37]
	v_mfma_f32_16x16x32_bf16 v[30:33], v[144:147], v[172:175], v[30:33]
	v_mfma_f32_16x16x32_bf16 v[180:183], v[148:151], v[152:155], v[46:49]
	v_mfma_f32_16x16x32_bf16 v[202:205], v[148:151], v[160:163], v[38:41]
	v_mfma_f32_16x16x32_bf16 v[134:137], v[148:151], v[176:179], v[30:33]
	s_setprio 0
	s_setprio 1
	v_mfma_f32_16x16x32_bf16 v[26:29], v[98:101], v[70:73], v[26:29]
	v_mfma_f32_16x16x32_bf16 v[18:21], v[98:101], v[90:93], v[18:21]
	v_mfma_f32_16x16x32_bf16 v[10:13], v[98:101], v[156:159], v[10:13]
	v_mfma_f32_16x16x32_bf16 v[6:9], v[188:191], v[156:159], v[6:9]
	v_mfma_f32_16x16x32_bf16 v[2:5], v[98:101], v[172:175], v[2:5]
	v_mfma_f32_16x16x32_bf16 v[26:29], v[184:187], v[78:81], v[26:29]
	v_mfma_f32_16x16x32_bf16 v[22:25], v[188:191], v[70:73], v[22:25]
	v_mfma_f32_16x16x32_bf16 v[18:21], v[184:187], v[152:155], v[18:21]
	v_mfma_f32_16x16x32_bf16 v[14:17], v[188:191], v[90:93], v[14:17]
	v_mfma_f32_16x16x32_bf16 v[10:13], v[184:187], v[160:163], v[10:13]
	v_mfma_f32_16x16x32_bf16 v[206:209], v[192:195], v[160:163], v[6:9]
	v_mfma_f32_16x16x32_bf16 v[2:5], v[184:187], v[176:179], v[2:5]
	v_mfma_f32_16x16x32_bf16 v[6:9], v[188:191], v[172:175], v[74:77]
	v_mfma_f32_16x16x32_bf16 v[138:141], v[192:195], v[78:81], v[22:25]
	v_mfma_f32_16x16x32_bf16 v[144:147], v[192:195], v[152:155], v[14:17]
	v_mfma_f32_16x16x32_bf16 v[172:175], v[192:195], v[176:179], v[6:9]
	s_setprio 0
	v_add_u32_e32 v22, 0x18000, v143
	s_barrier
	s_nop 1
	ds_read_b128 v[6:9], v22
	ds_read_b128 v[14:17], v22 offset:1024
	ds_read_b128 v[176:179], v22 offset:2048
	ds_read_b128 v[184:187], v22 offset:3072
	ds_read_b128 v[22:25], v142 offset:32768
	ds_read_b128 v[30:33], v142 offset:33792
	ds_read_b128 v[38:41], v142 offset:34816
	ds_read_b128 v[46:49], v142 offset:35840
	ds_read_b128 v[74:77], v142 offset:36864
	ds_read_b128 v[188:191], v142 offset:37888
	ds_read_b128 v[192:195], v142 offset:38912
	ds_read_b128 v[210:213], v142 offset:39936
	s_waitcnt vmcnt(2)
	s_barrier
	s_waitcnt lgkmcnt(0)
	s_setprio 1
	s_waitcnt lgkmcnt(0)
	v_mfma_f32_16x16x32_bf16 v[70:73], v[6:9], v[22:25], v[126:129]
	v_mfma_f32_16x16x32_bf16 v[152:155], v[14:17], v[30:33], v[70:73]
	v_mfma_f32_16x16x32_bf16 v[70:73], v[176:179], v[22:25], v[122:125]
	v_mfma_f32_16x16x32_bf16 v[160:163], v[184:187], v[30:33], v[70:73]
	v_mfma_f32_16x16x32_bf16 v[70:73], v[6:9], v[38:41], v[118:121]
	v_mfma_f32_16x16x32_bf16 v[122:125], v[14:17], v[46:49], v[70:73]
	v_mfma_f32_16x16x32_bf16 v[70:73], v[176:179], v[38:41], v[114:117]
	v_mfma_f32_16x16x32_bf16 v[114:117], v[184:187], v[46:49], v[70:73]
	v_mfma_f32_16x16x32_bf16 v[70:73], v[6:9], v[74:77], v[110:113]
	v_mfma_f32_16x16x32_bf16 v[98:101], v[14:17], v[188:191], v[70:73]
	v_mfma_f32_16x16x32_bf16 v[70:73], v[176:179], v[74:77], v[106:109]
	v_mfma_f32_16x16x32_bf16 v[90:93], v[184:187], v[188:191], v[70:73]
	v_mfma_f32_16x16x32_bf16 v[70:73], v[6:9], v[192:195], v[102:105]
	v_mfma_f32_16x16x32_bf16 v[78:81], v[14:17], v[210:213], v[70:73]
	v_mfma_f32_16x16x32_bf16 v[70:73], v[176:179], v[192:195], v[130:133]
	v_mfma_f32_16x16x32_bf16 v[70:73], v[184:187], v[210:213], v[70:73]
	s_setprio 0
	v_add_u32_e32 v102, 0x1c000, v143
	s_barrier
	ds_read_b128 v[106:109], v102
	ds_read_b128 v[110:113], v102 offset:1024
	ds_read_b128 v[130:133], v102 offset:2048
	ds_read_b128 v[214:217], v102 offset:3072
	s_waitcnt vmcnt(0)
	s_barrier
	s_waitcnt lgkmcnt(0)
	s_setprio 1
	s_waitcnt lgkmcnt(0)
	v_mfma_f32_16x16x32_bf16 v[94:97], v[106:109], v[22:25], v[94:97]
	v_mfma_f32_16x16x32_bf16 v[22:25], v[130:133], v[22:25], v[198:201]
	v_mfma_f32_16x16x32_bf16 v[148:151], v[214:217], v[30:33], v[22:25]
	v_mfma_f32_16x16x32_bf16 v[22:25], v[106:109], v[38:41], v[86:89]
	v_mfma_f32_16x16x32_bf16 v[126:129], v[110:113], v[46:49], v[22:25]
	v_mfma_f32_16x16x32_bf16 v[22:25], v[130:133], v[38:41], v[82:85]
	v_mfma_f32_16x16x32_bf16 v[118:121], v[214:217], v[46:49], v[22:25]
	v_mfma_f32_16x16x32_bf16 v[22:25], v[106:109], v[74:77], v[164:167]
	v_mfma_f32_16x16x32_bf16 v[102:105], v[110:113], v[188:191], v[22:25]
	v_mfma_f32_16x16x32_bf16 v[22:25], v[130:133], v[74:77], v[168:171]
	v_mfma_f32_16x16x32_bf16 v[156:159], v[110:113], v[30:33], v[94:97]
	v_mfma_f32_16x16x32_bf16 v[94:97], v[214:217], v[188:191], v[22:25]
	v_mfma_f32_16x16x32_bf16 v[22:25], v[106:109], v[192:195], v[66:69]
	v_mfma_f32_16x16x32_bf16 v[82:85], v[110:113], v[210:213], v[22:25]
	v_mfma_f32_16x16x32_bf16 v[22:25], v[130:133], v[192:195], v[62:65]
	v_mfma_f32_16x16x32_bf16 v[74:77], v[214:217], v[210:213], v[22:25]
	s_setprio 0
	s_barrier
	ds_read_b128 v[66:69], v142 offset:49152
	ds_read_b128 v[86:89], v142 offset:50176
	ds_read_b128 v[164:167], v142 offset:51200
	ds_read_b128 v[168:171], v142 offset:52224
	ds_read_b128 v[188:191], v142 offset:53248
	ds_read_b128 v[192:195], v142 offset:54272
	ds_read_b128 v[198:201], v142 offset:55296
	ds_read_b128 v[210:213], v142 offset:56320
	s_barrier
	s_waitcnt lgkmcnt(0)
	s_setprio 1
	s_waitcnt lgkmcnt(0)
	v_mfma_f32_16x16x32_bf16 v[22:25], v[6:9], v[66:69], v[58:61]
	v_mfma_f32_16x16x32_bf16 v[62:65], v[14:17], v[86:89], v[22:25]
	v_mfma_f32_16x16x32_bf16 v[22:25], v[176:179], v[66:69], v[54:57]
	v_mfma_f32_16x16x32_bf16 v[54:57], v[184:187], v[86:89], v[22:25]
	v_mfma_f32_16x16x32_bf16 v[22:25], v[6:9], v[164:167], v[50:53]
	v_mfma_f32_16x16x32_bf16 v[46:49], v[14:17], v[168:171], v[22:25]
	v_mfma_f32_16x16x32_bf16 v[22:25], v[176:179], v[164:167], v[180:183]
	v_mfma_f32_16x16x32_bf16 v[38:41], v[184:187], v[168:171], v[22:25]
	v_mfma_f32_16x16x32_bf16 v[22:25], v[6:9], v[188:191], v[42:45]
	v_mfma_f32_16x16x32_bf16 v[6:9], v[6:9], v[198:201], v[34:37]
	v_mfma_f32_16x16x32_bf16 v[30:33], v[14:17], v[192:195], v[22:25]
	v_mfma_f32_16x16x32_bf16 v[22:25], v[176:179], v[188:191], v[202:205]
	v_mfma_f32_16x16x32_bf16 v[14:17], v[14:17], v[210:213], v[6:9]
	v_mfma_f32_16x16x32_bf16 v[6:9], v[176:179], v[198:201], v[134:137]
	v_mfma_f32_16x16x32_bf16 v[22:25], v[184:187], v[192:195], v[22:25]
	v_mfma_f32_16x16x32_bf16 v[6:9], v[184:187], v[210:213], v[6:9]
	s_setprio 0
	s_setprio 1
	v_mfma_f32_16x16x32_bf16 v[26:29], v[106:109], v[66:69], v[26:29]
	v_mfma_f32_16x16x32_bf16 v[58:61], v[110:113], v[86:89], v[26:29]
	v_mfma_f32_16x16x32_bf16 v[26:29], v[130:133], v[66:69], v[138:141]
	v_mfma_f32_16x16x32_bf16 v[18:21], v[106:109], v[164:167], v[18:21]
	v_mfma_f32_16x16x32_bf16 v[10:13], v[106:109], v[188:191], v[10:13]
	v_mfma_f32_16x16x32_bf16 v[50:53], v[214:217], v[86:89], v[26:29]
	v_mfma_f32_16x16x32_bf16 v[42:45], v[110:113], v[168:171], v[18:21]
	v_mfma_f32_16x16x32_bf16 v[18:21], v[130:133], v[164:167], v[144:147]
	v_mfma_f32_16x16x32_bf16 v[26:29], v[110:113], v[192:195], v[10:13]
	v_mfma_f32_16x16x32_bf16 v[10:13], v[130:133], v[188:191], v[206:209]
	v_mfma_f32_16x16x32_bf16 v[2:5], v[106:109], v[198:201], v[2:5]
	v_mfma_f32_16x16x32_bf16 v[34:37], v[214:217], v[168:171], v[18:21]
	v_mfma_f32_16x16x32_bf16 v[18:21], v[214:217], v[192:195], v[10:13]
	v_mfma_f32_16x16x32_bf16 v[10:13], v[110:113], v[210:213], v[2:5]
	v_mfma_f32_16x16x32_bf16 v[2:5], v[130:133], v[198:201], v[172:175]
	v_mfma_f32_16x16x32_bf16 v[2:5], v[214:217], v[210:213], v[2:5]
	s_setprio 0
	s_cmpk_lt_u32 s2, 0x100
	s_movk_i32 s75, 0x410
	s_movk_i32 s76, 0xfbfc
	s_barrier
	s_cbranch_scc0 .LBB0_98
	s_barrier

.LBB0_160:
	v_and_b32_e32 v17, 15, v13
	v_and_b32_e32 v18, 48, v13
	v_lshlrev_b32_e32 v13, 2, v13
	v_lshlrev_b32_e32 v17, 6, v17
	v_and_b32_e32 v13, 32, v13
	s_lshl_b32 s68, s75, 12
	v_or_b32_e32 v19, v17, v18
	v_bitop3_b32 v17, v17, v13, v18 bitop3:0x36
	s_lshl_b32 s69, s83, 13
	s_and_b32 s68, s68, 0x3000
	s_add_i32 m0, s43, 0x18000
	v_lshl_add_u64 v[6:7], v[6:7], 0, s[48:49]
	v_bitop3_b32 v13, v19, s69, v13 bitop3:0xde
	v_or_b32_e32 v143, s68, v17
	global_load_lds_dwordx4 v[6:7], off
	v_lshl_add_u64 v[6:7], v[8:9], 0, s[48:49]
	s_add_i32 m0, s43, 0x1a000
	s_add_i32 s68, s43, 0x8000
	s_add_i32 s69, s43, 0xa000
	global_load_lds_dwordx4 v[6:7], off
	v_lshl_add_u64 v[4:5], v[4:5], 0, s[48:49]
	s_mov_b32 m0, s68
	s_add_u32 s44, s44, 0x40080
	global_load_lds_dwordx4 v[4:5], off
	v_lshl_add_u64 v[2:3], v[2:3], 0, s[48:49]
	s_mov_b32 m0, s69
	s_addc_u32 s45, s45, 0
	global_load_lds_dwordx4 v[2:3], off
	s_add_i32 m0, s43, 0x1c000
	v_lshl_add_u64 v[2:3], s[44:45], 0, v[130:131]
	global_load_lds_dwordx4 v[2:3], off
	v_lshl_add_u64 v[2:3], s[44:45], 0, v[132:133]
	s_add_i32 m0, s43, 0x1e000
	v_readlane_b32 s18, v253, 1
	global_load_lds_dwordx4 v[2:3], off
	v_lshlrev_b32_e32 v2, 14, v10
	v_and_b32_e32 v2, 0xffff8000, v2
	v_readlane_b32 s19, v253, 2
	s_add_u32 s40, s18, s40
	v_lshlrev_b32_e32 v4, 14, v11
	v_lshl_add_u32 v2, v12, 11, v2
	v_and_b32_e32 v3, 1, v10
	s_addc_u32 s41, s19, s41
	v_and_b32_e32 v4, 0xffff8000, v4
	v_lshl_or_b32 v2, v3, 6, v2
	v_lshl_add_u32 v4, v15, 11, v4
	v_and_b32_e32 v5, 1, v11
	s_add_u32 s16, s18, s16
	s_waitcnt vmcnt(6)
	v_lshl_add_u32 v2, v14, 1, v2
	v_mov_b32_e32 v3, v196
	v_lshl_or_b32 v4, v5, 6, v4
	s_addc_u32 s17, s19, s17
	v_lshl_add_u64 v[134:135], s[40:41], 0, v[2:3]
	v_lshl_add_u32 v4, v16, 1, v4
	v_mov_b32_e32 v5, v196
	v_lshl_add_u64 v[138:139], s[16:17], 0, v[2:3]
	v_mov_b32_e32 v2, 0
	v_lshl_add_u64 v[136:137], s[40:41], 0, v[4:5]
	v_lshl_add_u64 v[140:141], s[16:17], 0, v[4:5]
	s_mov_b32 s16, -2
	v_add_u32_e32 v142, 0, v13
	v_mov_b32_e32 v3, v2
	v_mov_b32_e32 v4, v2
	v_mov_b32_e32 v5, v2
	v_mov_b32_e32 v6, v2
	v_mov_b32_e32 v7, v2
	v_mov_b32_e32 v8, v2
	v_mov_b32_e32 v9, v2
	v_mov_b32_e32 v10, v2
	v_mov_b32_e32 v11, v2
	v_mov_b32_e32 v12, v2
	v_mov_b32_e32 v13, v2
	v_mov_b32_e32 v14, v2
	v_mov_b32_e32 v15, v2
	v_mov_b32_e32 v16, v2
	v_mov_b32_e32 v17, v2
	v_mov_b32_e32 v18, v2
	v_mov_b32_e32 v19, v2
	v_mov_b32_e32 v20, v2
	v_mov_b32_e32 v21, v2
	v_mov_b32_e32 v22, v2
	v_mov_b32_e32 v23, v2
	v_mov_b32_e32 v24, v2
	v_mov_b32_e32 v25, v2
	v_mov_b32_e32 v26, v2
	v_mov_b32_e32 v27, v2
	v_mov_b32_e32 v28, v2
	v_mov_b32_e32 v29, v2
	v_mov_b32_e32 v30, v2
	v_mov_b32_e32 v31, v2
	v_mov_b32_e32 v32, v2
	v_mov_b32_e32 v33, v2
	v_mov_b32_e32 v34, v2
	v_mov_b32_e32 v35, v2
	v_mov_b32_e32 v36, v2
	v_mov_b32_e32 v37, v2
	v_mov_b32_e32 v38, v2
	v_mov_b32_e32 v39, v2
	v_mov_b32_e32 v40, v2
	v_mov_b32_e32 v41, v2
	v_mov_b32_e32 v42, v2
	v_mov_b32_e32 v43, v2
	v_mov_b32_e32 v44, v2
	v_mov_b32_e32 v45, v2
	v_mov_b32_e32 v46, v2
	v_mov_b32_e32 v47, v2
	v_mov_b32_e32 v48, v2
	v_mov_b32_e32 v49, v2
	v_mov_b32_e32 v50, v2
	v_mov_b32_e32 v51, v2
	v_mov_b32_e32 v52, v2
	v_mov_b32_e32 v53, v2
	v_mov_b32_e32 v54, v2
	v_mov_b32_e32 v55, v2
	v_mov_b32_e32 v56, v2
	v_mov_b32_e32 v57, v2
	v_mov_b32_e32 v58, v2
	v_mov_b32_e32 v59, v2
	v_mov_b32_e32 v60, v2
	v_mov_b32_e32 v61, v2
	v_mov_b32_e32 v62, v2
	v_mov_b32_e32 v63, v2
	v_mov_b32_e32 v64, v2
	v_mov_b32_e32 v65, v2
	v_mov_b32_e32 v78, v2
	v_mov_b32_e32 v79, v2
	v_mov_b32_e32 v80, v2
	v_mov_b32_e32 v81, v2
	v_mov_b32_e32 v90, v2
	v_mov_b32_e32 v91, v2
	v_mov_b32_e32 v92, v2
	v_mov_b32_e32 v93, v2
	v_mov_b32_e32 v94, v2
	v_mov_b32_e32 v95, v2
	v_mov_b32_e32 v96, v2
	v_mov_b32_e32 v97, v2
	v_mov_b32_e32 v98, v2
	v_mov_b32_e32 v99, v2
	v_mov_b32_e32 v100, v2
	v_mov_b32_e32 v101, v2
	v_mov_b32_e32 v102, v2
	v_mov_b32_e32 v103, v2
	v_mov_b32_e32 v104, v2
	v_mov_b32_e32 v105, v2
	v_mov_b32_e32 v106, v2
	v_mov_b32_e32 v107, v2
	v_mov_b32_e32 v108, v2
	v_mov_b32_e32 v109, v2
	v_mov_b32_e32 v110, v2
	v_mov_b32_e32 v111, v2
	v_mov_b32_e32 v112, v2
	v_mov_b32_e32 v113, v2
	v_mov_b32_e32 v114, v2
	v_mov_b32_e32 v115, v2
	v_mov_b32_e32 v116, v2
	v_mov_b32_e32 v117, v2
	v_mov_b32_e32 v118, v2
	v_mov_b32_e32 v119, v2
	v_mov_b32_e32 v120, v2
	v_mov_b32_e32 v121, v2
	v_mov_b32_e32 v122, v2
	v_mov_b32_e32 v123, v2
	v_mov_b32_e32 v124, v2
	v_mov_b32_e32 v125, v2
	v_mov_b32_e32 v126, v2
	v_mov_b32_e32 v127, v2
	v_mov_b32_e32 v128, v2
	v_mov_b32_e32 v129, v2
	v_mov_b32_e32 v66, v2
	v_mov_b32_e32 v67, v2
	v_mov_b32_e32 v68, v2
	v_mov_b32_e32 v69, v2
	v_mov_b32_e32 v70, v2
	v_mov_b32_e32 v71, v2
	v_mov_b32_e32 v72, v2
	v_mov_b32_e32 v73, v2
	v_mov_b32_e32 v74, v2
	v_mov_b32_e32 v75, v2
	v_mov_b32_e32 v76, v2
	v_mov_b32_e32 v77, v2
	v_mov_b32_e32 v82, v2
	v_mov_b32_e32 v83, v2
	v_mov_b32_e32 v84, v2
	v_mov_b32_e32 v85, v2
	v_mov_b32_e32 v86, v2
	v_mov_b32_e32 v87, v2
	v_mov_b32_e32 v88, v2
	v_mov_b32_e32 v89, v2
	s_barrier
	v_add_u32_e32 v156, 0x10000, v143
	ds_read_b128 v[144:147], v156
	ds_read_b128 v[148:151], v156 offset:1024
	ds_read_b128 v[152:155], v156 offset:2048
	ds_read_b128 v[156:159], v156 offset:3072
.LBB0_161:
	s_add_i32 s41, 0, 0x10000
	v_lshl_add_u64 v[210:211], v[138:139], 0, s[14:15]
	s_add_i32 s40, s43, 0xc000
	v_lshl_add_u64 v[192:193], v[210:211], 0, s[20:21]
	s_mov_b32 m0, s40
	v_lshl_add_u64 v[212:213], v[140:141], 0, s[14:15]
	s_add_i32 s17, s43, 0xe000
	ds_read_b128 v[160:163], v142
	ds_read_b128 v[164:167], v142 offset:1024
	ds_read_b128 v[168:171], v142 offset:2048
	ds_read_b128 v[172:175], v142 offset:3072
	ds_read_b128 v[176:179], v142 offset:4096
	ds_read_b128 v[180:183], v142 offset:5120
	ds_read_b128 v[184:187], v142 offset:6144
	ds_read_b128 v[188:191], v142 offset:7168
	global_load_lds_dwordx4 v[192:193], off
	v_lshl_add_u64 v[192:193], v[212:213], 0, s[20:21]
	s_mov_b32 m0, s17
	s_nop 0
	global_load_lds_dwordx4 v[192:193], off
	s_waitcnt lgkmcnt(8)
	s_barrier
	s_waitcnt lgkmcnt(0)
	s_setprio 1
	s_waitcnt lgkmcnt(0)
	v_mfma_f32_16x16x32_bf16 v[126:129], v[144:147], v[160:163], v[126:129]
	v_mfma_f32_16x16x32_bf16 v[122:125], v[152:155], v[160:163], v[122:125]
	v_mfma_f32_16x16x32_bf16 v[118:121], v[144:147], v[168:171], v[118:121]
	v_mfma_f32_16x16x32_bf16 v[114:117], v[152:155], v[168:171], v[114:117]
	v_mfma_f32_16x16x32_bf16 v[110:113], v[144:147], v[176:179], v[110:113]
	v_mfma_f32_16x16x32_bf16 v[106:109], v[152:155], v[176:179], v[106:109]
	v_mfma_f32_16x16x32_bf16 v[102:105], v[144:147], v[184:187], v[102:105]
	v_mfma_f32_16x16x32_bf16 v[98:101], v[152:155], v[184:187], v[98:101]
	v_mfma_f32_16x16x32_bf16 v[126:129], v[148:151], v[164:167], v[126:129]
	v_mfma_f32_16x16x32_bf16 v[122:125], v[156:159], v[164:167], v[122:125]
	v_mfma_f32_16x16x32_bf16 v[118:121], v[148:151], v[172:175], v[118:121]
	v_mfma_f32_16x16x32_bf16 v[114:117], v[156:159], v[172:175], v[114:117]
	v_mfma_f32_16x16x32_bf16 v[110:113], v[148:151], v[180:183], v[110:113]
	v_mfma_f32_16x16x32_bf16 v[106:109], v[156:159], v[180:183], v[106:109]
	v_mfma_f32_16x16x32_bf16 v[102:105], v[148:151], v[188:191], v[102:105]
	v_mfma_f32_16x16x32_bf16 v[98:101], v[156:159], v[188:191], v[98:101]
	s_setprio 0
	s_barrier
	s_add_i32 s44, 0, 0x14000
	v_lshl_add_u64 v[214:215], v[134:135], 0, s[14:15]
	s_add_i32 s41, s41, s37
	v_add_u32_e32 v197, s44, v143
	v_lshl_add_u64 v[216:217], v[214:215], 0, s[22:23]
	s_mov_b32 m0, s41
	ds_read_b128 v[192:195], v197
	ds_read_b128 v[198:201], v197 offset:1024
	ds_read_b128 v[202:205], v197 offset:2048
	ds_read_b128 v[206:209], v197 offset:3072
	global_load_lds_dwordx4 v[216:217], off
	v_lshl_add_u64 v[216:217], v[136:137], 0, s[14:15]
	v_lshl_add_u64 v[218:219], v[216:217], 0, s[22:23]
	s_add_i32 m0, s41, 0x2000
	s_nop 0
	global_load_lds_dwordx4 v[218:219], off
	s_barrier
	s_waitcnt lgkmcnt(0)
	s_setprio 1
	s_waitcnt lgkmcnt(0)
	v_mfma_f32_16x16x32_bf16 v[94:97], v[192:195], v[160:163], v[94:97]
	v_mfma_f32_16x16x32_bf16 v[90:93], v[202:205], v[160:163], v[90:93]
	v_mfma_f32_16x16x32_bf16 v[78:81], v[192:195], v[168:171], v[78:81]
	v_mfma_f32_16x16x32_bf16 v[62:65], v[202:205], v[168:171], v[62:65]
	v_mfma_f32_16x16x32_bf16 v[58:61], v[192:195], v[176:179], v[58:61]
	v_mfma_f32_16x16x32_bf16 v[54:57], v[202:205], v[176:179], v[54:57]
	v_mfma_f32_16x16x32_bf16 v[50:53], v[192:195], v[184:187], v[50:53]
	v_mfma_f32_16x16x32_bf16 v[46:49], v[202:205], v[184:187], v[46:49]
	v_mfma_f32_16x16x32_bf16 v[94:97], v[198:201], v[164:167], v[94:97]
	v_mfma_f32_16x16x32_bf16 v[90:93], v[206:209], v[164:167], v[90:93]
	v_mfma_f32_16x16x32_bf16 v[78:81], v[198:201], v[172:175], v[78:81]
	v_mfma_f32_16x16x32_bf16 v[62:65], v[206:209], v[172:175], v[62:65]
	v_mfma_f32_16x16x32_bf16 v[58:61], v[198:201], v[180:183], v[58:61]
	v_mfma_f32_16x16x32_bf16 v[54:57], v[206:209], v[180:183], v[54:57]
	v_mfma_f32_16x16x32_bf16 v[50:53], v[198:201], v[188:191], v[50:53]
	v_mfma_f32_16x16x32_bf16 v[46:49], v[206:209], v[188:191], v[46:49]
	s_setprio 0
	s_mov_b32 m0, s43
	v_lshl_add_u64 v[218:219], v[210:211], 0, s[24:25]
	s_barrier
	ds_read_b128 v[160:163], v142 offset:16384
	ds_read_b128 v[164:167], v142 offset:17408
	ds_read_b128 v[168:171], v142 offset:18432
	ds_read_b128 v[172:175], v142 offset:19456
	ds_read_b128 v[176:179], v142 offset:20480
	ds_read_b128 v[180:183], v142 offset:21504
	ds_read_b128 v[184:187], v142 offset:22528
	ds_read_b128 v[188:191], v142 offset:23552
	global_load_lds_dwordx4 v[218:219], off
	v_lshl_add_u64 v[218:219], v[212:213], 0, s[24:25]
	s_mov_b32 m0, s73
	s_nop 0
	global_load_lds_dwordx4 v[218:219], off
	s_waitcnt vmcnt(10)
	s_barrier
	s_waitcnt lgkmcnt(0)
	s_setprio 1
	s_waitcnt lgkmcnt(0)
	v_mfma_f32_16x16x32_bf16 v[42:45], v[144:147], v[160:163], v[42:45]
	v_mfma_f32_16x16x32_bf16 v[38:41], v[152:155], v[160:163], v[38:41]
	v_mfma_f32_16x16x32_bf16 v[34:37], v[144:147], v[168:171], v[34:37]
	v_mfma_f32_16x16x32_bf16 v[30:33], v[152:155], v[168:171], v[30:33]
	v_mfma_f32_16x16x32_bf16 v[26:29], v[144:147], v[176:179], v[26:29]
	v_mfma_f32_16x16x32_bf16 v[22:25], v[152:155], v[176:179], v[22:25]
	v_mfma_f32_16x16x32_bf16 v[18:21], v[144:147], v[184:187], v[18:21]
	v_mfma_f32_16x16x32_bf16 v[14:17], v[152:155], v[184:187], v[14:17]
	v_mfma_f32_16x16x32_bf16 v[42:45], v[148:151], v[164:167], v[42:45]
	v_mfma_f32_16x16x32_bf16 v[38:41], v[156:159], v[164:167], v[38:41]
	v_mfma_f32_16x16x32_bf16 v[34:37], v[148:151], v[172:175], v[34:37]
	v_mfma_f32_16x16x32_bf16 v[30:33], v[156:159], v[172:175], v[30:33]
	v_mfma_f32_16x16x32_bf16 v[26:29], v[148:151], v[180:183], v[26:29]
	v_mfma_f32_16x16x32_bf16 v[22:25], v[156:159], v[180:183], v[22:25]
	v_mfma_f32_16x16x32_bf16 v[18:21], v[148:151], v[188:191], v[18:21]
	v_mfma_f32_16x16x32_bf16 v[14:17], v[156:159], v[188:191], v[14:17]
	s_setprio 0
	s_barrier
	s_add_i32 s41, s44, s37
	v_lshl_add_u64 v[144:145], v[214:215], 0, s[26:27]
	s_mov_b32 m0, s41
	s_nop 0
	global_load_lds_dwordx4 v[144:145], off
	v_lshl_add_u64 v[144:145], v[216:217], 0, s[26:27]
	s_add_i32 m0, s41, 0x2000
	s_nop 0
	global_load_lds_dwordx4 v[144:145], off
	v_add_u32_e32 v156, 0x18000, v143
	ds_read_b128 v[144:147], v156
	ds_read_b128 v[148:151], v156 offset:1024
	ds_read_b128 v[152:155], v156 offset:2048
	ds_read_b128 v[156:159], v156 offset:3072
	s_waitcnt vmcnt(6)
	s_barrier
	s_setprio 1
	v_mfma_f32_16x16x32_bf16 v[10:13], v[192:195], v[160:163], v[10:13]
	v_mfma_f32_16x16x32_bf16 v[6:9], v[202:205], v[160:163], v[6:9]
	v_mfma_f32_16x16x32_bf16 v[2:5], v[192:195], v[168:171], v[2:5]
	v_mfma_f32_16x16x32_bf16 v[66:69], v[202:205], v[168:171], v[66:69]
	v_mfma_f32_16x16x32_bf16 v[70:73], v[192:195], v[176:179], v[70:73]
	v_mfma_f32_16x16x32_bf16 v[74:77], v[202:205], v[176:179], v[74:77]
	v_mfma_f32_16x16x32_bf16 v[82:85], v[192:195], v[184:187], v[82:85]
	v_mfma_f32_16x16x32_bf16 v[86:89], v[202:205], v[184:187], v[86:89]
	v_mfma_f32_16x16x32_bf16 v[10:13], v[198:201], v[164:167], v[10:13]
	v_mfma_f32_16x16x32_bf16 v[6:9], v[206:209], v[164:167], v[6:9]
	v_mfma_f32_16x16x32_bf16 v[2:5], v[198:201], v[172:175], v[2:5]
	v_mfma_f32_16x16x32_bf16 v[66:69], v[206:209], v[172:175], v[66:69]
	v_mfma_f32_16x16x32_bf16 v[70:73], v[198:201], v[180:183], v[70:73]
	v_mfma_f32_16x16x32_bf16 v[74:77], v[206:209], v[180:183], v[74:77]
	v_mfma_f32_16x16x32_bf16 v[82:85], v[198:201], v[188:191], v[82:85]
	v_mfma_f32_16x16x32_bf16 v[86:89], v[206:209], v[188:191], v[86:89]
	s_setprio 0
	s_add_i32 s41, 0, 0x18000
	s_barrier
	s_mov_b32 m0, s79
	v_lshl_add_u64 v[192:193], v[210:211], 0, s[28:29]
	ds_read_b128 v[160:163], v142 offset:32768
	ds_read_b128 v[164:167], v142 offset:33792
	ds_read_b128 v[168:171], v142 offset:34816
	ds_read_b128 v[172:175], v142 offset:35840
	ds_read_b128 v[176:179], v142 offset:36864
	ds_read_b128 v[180:183], v142 offset:37888
	ds_read_b128 v[184:187], v142 offset:38912
	ds_read_b128 v[188:191], v142 offset:39936
	global_load_lds_dwordx4 v[192:193], off
	v_lshl_add_u64 v[192:193], v[212:213], 0, s[28:29]
	s_mov_b32 m0, s78
	s_nop 0
	global_load_lds_dwordx4 v[192:193], off
	s_waitcnt lgkmcnt(8)
	s_barrier
	s_waitcnt lgkmcnt(0)
	s_setprio 1
	s_waitcnt lgkmcnt(0)
	v_mfma_f32_16x16x32_bf16 v[126:129], v[144:147], v[160:163], v[126:129]
	v_mfma_f32_16x16x32_bf16 v[122:125], v[152:155], v[160:163], v[122:125]
	v_mfma_f32_16x16x32_bf16 v[118:121], v[144:147], v[168:171], v[118:121]
	v_mfma_f32_16x16x32_bf16 v[114:117], v[152:155], v[168:171], v[114:117]
	v_mfma_f32_16x16x32_bf16 v[110:113], v[144:147], v[176:179], v[110:113]
	v_mfma_f32_16x16x32_bf16 v[106:109], v[152:155], v[176:179], v[106:109]
	v_mfma_f32_16x16x32_bf16 v[102:105], v[144:147], v[184:187], v[102:105]
	v_mfma_f32_16x16x32_bf16 v[98:101], v[152:155], v[184:187], v[98:101]
	v_mfma_f32_16x16x32_bf16 v[126:129], v[148:151], v[164:167], v[126:129]
	v_mfma_f32_16x16x32_bf16 v[122:125], v[156:159], v[164:167], v[122:125]
	v_mfma_f32_16x16x32_bf16 v[118:121], v[148:151], v[172:175], v[118:121]
	v_mfma_f32_16x16x32_bf16 v[114:117], v[156:159], v[172:175], v[114:117]
	v_mfma_f32_16x16x32_bf16 v[110:113], v[148:151], v[180:183], v[110:113]
	v_mfma_f32_16x16x32_bf16 v[106:109], v[156:159], v[180:183], v[106:109]
	v_mfma_f32_16x16x32_bf16 v[102:105], v[148:151], v[188:191], v[102:105]
	v_mfma_f32_16x16x32_bf16 v[98:101], v[156:159], v[188:191], v[98:101]
	s_setprio 0
	s_barrier
	s_add_i32 s44, 0, 0x1c000
	s_add_i32 s41, s41, s37
	v_add_u32_e32 v197, s44, v143
	v_lshl_add_u64 v[218:219], v[214:215], 0, s[30:31]
	s_mov_b32 m0, s41
	ds_read_b128 v[192:195], v197
	ds_read_b128 v[198:201], v197 offset:1024
	ds_read_b128 v[202:205], v197 offset:2048
	ds_read_b128 v[206:209], v197 offset:3072
	global_load_lds_dwordx4 v[218:219], off
	v_lshl_add_u64 v[218:219], v[216:217], 0, s[30:31]
	s_add_i32 m0, s41, 0x2000
	s_nop 0
	global_load_lds_dwordx4 v[218:219], off
	s_barrier
	s_waitcnt lgkmcnt(0)
	s_setprio 1
	s_waitcnt lgkmcnt(0)
	v_mfma_f32_16x16x32_bf16 v[94:97], v[192:195], v[160:163], v[94:97]
	v_mfma_f32_16x16x32_bf16 v[90:93], v[202:205], v[160:163], v[90:93]
	v_mfma_f32_16x16x32_bf16 v[78:81], v[192:195], v[168:171], v[78:81]
	v_mfma_f32_16x16x32_bf16 v[62:65], v[202:205], v[168:171], v[62:65]
	v_mfma_f32_16x16x32_bf16 v[58:61], v[192:195], v[176:179], v[58:61]
	v_mfma_f32_16x16x32_bf16 v[54:57], v[202:205], v[176:179], v[54:57]
	v_mfma_f32_16x16x32_bf16 v[50:53], v[192:195], v[184:187], v[50:53]
	v_mfma_f32_16x16x32_bf16 v[46:49], v[202:205], v[184:187], v[46:49]
	v_mfma_f32_16x16x32_bf16 v[94:97], v[198:201], v[164:167], v[94:97]
	v_mfma_f32_16x16x32_bf16 v[90:93], v[206:209], v[164:167], v[90:93]
	v_mfma_f32_16x16x32_bf16 v[78:81], v[198:201], v[172:175], v[78:81]
	v_mfma_f32_16x16x32_bf16 v[62:65], v[206:209], v[172:175], v[62:65]
	v_mfma_f32_16x16x32_bf16 v[58:61], v[198:201], v[180:183], v[58:61]
	v_mfma_f32_16x16x32_bf16 v[54:57], v[206:209], v[180:183], v[54:57]
	v_mfma_f32_16x16x32_bf16 v[50:53], v[198:201], v[188:191], v[50:53]
	v_mfma_f32_16x16x32_bf16 v[46:49], v[206:209], v[188:191], v[46:49]
	s_setprio 0
	s_mov_b32 m0, s68
	v_lshl_add_u64 v[210:211], v[210:211], 0, s[34:35]
	s_barrier
	ds_read_b128 v[160:163], v142 offset:49152
	ds_read_b128 v[164:167], v142 offset:50176
	ds_read_b128 v[168:171], v142 offset:51200
	ds_read_b128 v[172:175], v142 offset:52224
	ds_read_b128 v[176:179], v142 offset:53248
	ds_read_b128 v[180:183], v142 offset:54272
	ds_read_b128 v[184:187], v142 offset:55296
	ds_read_b128 v[188:191], v142 offset:56320
	global_load_lds_dwordx4 v[210:211], off
	v_lshl_add_u64 v[210:211], v[212:213], 0, s[34:35]
	s_mov_b32 m0, s69
	s_nop 0
	global_load_lds_dwordx4 v[210:211], off
	s_waitcnt vmcnt(10)
	s_barrier
	s_waitcnt lgkmcnt(0)
	s_setprio 1
	s_waitcnt lgkmcnt(0)
	v_mfma_f32_16x16x32_bf16 v[42:45], v[144:147], v[160:163], v[42:45]
	v_mfma_f32_16x16x32_bf16 v[38:41], v[152:155], v[160:163], v[38:41]
	v_mfma_f32_16x16x32_bf16 v[34:37], v[144:147], v[168:171], v[34:37]
	v_mfma_f32_16x16x32_bf16 v[30:33], v[152:155], v[168:171], v[30:33]
	v_mfma_f32_16x16x32_bf16 v[26:29], v[144:147], v[176:179], v[26:29]
	v_mfma_f32_16x16x32_bf16 v[22:25], v[152:155], v[176:179], v[22:25]
	v_mfma_f32_16x16x32_bf16 v[18:21], v[144:147], v[184:187], v[18:21]
	v_mfma_f32_16x16x32_bf16 v[14:17], v[152:155], v[184:187], v[14:17]
	v_mfma_f32_16x16x32_bf16 v[42:45], v[148:151], v[164:167], v[42:45]
	v_mfma_f32_16x16x32_bf16 v[38:41], v[156:159], v[164:167], v[38:41]
	v_mfma_f32_16x16x32_bf16 v[34:37], v[148:151], v[172:175], v[34:37]
	v_mfma_f32_16x16x32_bf16 v[30:33], v[156:159], v[172:175], v[30:33]
	v_mfma_f32_16x16x32_bf16 v[26:29], v[148:151], v[180:183], v[26:29]
	v_mfma_f32_16x16x32_bf16 v[22:25], v[156:159], v[180:183], v[22:25]
	v_mfma_f32_16x16x32_bf16 v[18:21], v[148:151], v[188:191], v[18:21]
	v_mfma_f32_16x16x32_bf16 v[14:17], v[156:159], v[188:191], v[14:17]
	s_setprio 0
	s_barrier
	s_add_i32 s41, s44, s37
	v_lshl_add_u64 v[144:145], v[214:215], 0, s[92:93]
	s_mov_b32 m0, s41
	s_nop 0
	global_load_lds_dwordx4 v[144:145], off
	v_lshl_add_u64 v[144:145], v[216:217], 0, s[92:93]
	s_add_i32 m0, s41, 0x2000
	s_nop 0
	global_load_lds_dwordx4 v[144:145], off
	v_add_u32_e32 v156, 0x10000, v143
	ds_read_b128 v[144:147], v156
	ds_read_b128 v[148:151], v156 offset:1024
	ds_read_b128 v[152:155], v156 offset:2048
	ds_read_b128 v[156:159], v156 offset:3072
	s_waitcnt vmcnt(6)
	s_barrier
	s_setprio 1
	v_mfma_f32_16x16x32_bf16 v[10:13], v[192:195], v[160:163], v[10:13]
	v_mfma_f32_16x16x32_bf16 v[6:9], v[202:205], v[160:163], v[6:9]
	v_mfma_f32_16x16x32_bf16 v[2:5], v[192:195], v[168:171], v[2:5]
	v_mfma_f32_16x16x32_bf16 v[66:69], v[202:205], v[168:171], v[66:69]
	v_mfma_f32_16x16x32_bf16 v[70:73], v[192:195], v[176:179], v[70:73]
	v_mfma_f32_16x16x32_bf16 v[74:77], v[202:205], v[176:179], v[74:77]
	v_mfma_f32_16x16x32_bf16 v[82:85], v[192:195], v[184:187], v[82:85]
	v_mfma_f32_16x16x32_bf16 v[86:89], v[202:205], v[184:187], v[86:89]
	v_mfma_f32_16x16x32_bf16 v[10:13], v[198:201], v[164:167], v[10:13]
	v_mfma_f32_16x16x32_bf16 v[6:9], v[206:209], v[164:167], v[6:9]
	v_mfma_f32_16x16x32_bf16 v[2:5], v[198:201], v[172:175], v[2:5]
	v_mfma_f32_16x16x32_bf16 v[66:69], v[206:209], v[172:175], v[66:69]
	v_mfma_f32_16x16x32_bf16 v[70:73], v[198:201], v[180:183], v[70:73]
	v_mfma_f32_16x16x32_bf16 v[74:77], v[206:209], v[180:183], v[74:77]
	v_mfma_f32_16x16x32_bf16 v[82:85], v[198:201], v[188:191], v[82:85]
	v_mfma_f32_16x16x32_bf16 v[86:89], v[206:209], v[188:191], v[86:89]
	s_setprio 0
	s_add_i32 s16, s16, 2
	v_lshl_add_u64 v[134:135], v[134:135], 0, s[98:99]
	v_lshl_add_u64 v[136:137], v[136:137], 0, s[98:99]
	v_lshl_add_u64 v[138:139], v[138:139], 0, s[98:99]
	s_cmp_gt_u32 s16, 11
	v_lshl_add_u64 v[140:141], v[140:141], 0, s[98:99]
	s_barrier
	s_cbranch_scc0 .LBB0_161
	s_waitcnt lgkmcnt(0)
	s_add_u32 s0, s0, 0x40780
	v_add_u32_e32 v143, 0, v143
	s_addc_u32 s1, s1, 0
	s_mov_b32 m0, s40
	v_add_u32_e32 v148, 0x10000, v143
	v_lshl_add_u64 v[130:131], s[0:1], 0, v[130:131]
	ds_read_b128 v[134:137], v148
	ds_read_b128 v[138:141], v148 offset:1024
	ds_read_b128 v[144:147], v148 offset:2048
	ds_read_b128 v[148:151], v148 offset:3072
	ds_read_b128 v[152:155], v142
	ds_read_b128 v[156:159], v142 offset:1024
	ds_read_b128 v[160:163], v142 offset:2048
	ds_read_b128 v[164:167], v142 offset:3072
	ds_read_b128 v[168:171], v142 offset:4096
	ds_read_b128 v[172:175], v142 offset:5120
	ds_read_b128 v[176:179], v142 offset:6144
	ds_read_b128 v[180:183], v142 offset:7168
	global_load_lds_dwordx4 v[130:131], off
	v_lshl_add_u64 v[130:131], s[0:1], 0, v[132:133]
	s_mov_b32 m0, s17
	s_nop 0
	global_load_lds_dwordx4 v[130:131], off
	s_barrier
	s_waitcnt lgkmcnt(0)
	s_setprio 1
	s_waitcnt lgkmcnt(0)
	v_mfma_f32_16x16x32_bf16 v[126:129], v[134:137], v[152:155], v[126:129]
	v_mfma_f32_16x16x32_bf16 v[122:125], v[144:147], v[152:155], v[122:125]
	v_mfma_f32_16x16x32_bf16 v[118:121], v[134:137], v[160:163], v[118:121]
	v_mfma_f32_16x16x32_bf16 v[114:117], v[144:147], v[160:163], v[114:117]
	v_mfma_f32_16x16x32_bf16 v[110:113], v[134:137], v[168:171], v[110:113]
	v_mfma_f32_16x16x32_bf16 v[106:109], v[144:147], v[168:171], v[106:109]
	v_mfma_f32_16x16x32_bf16 v[102:105], v[134:137], v[176:179], v[102:105]
	v_mfma_f32_16x16x32_bf16 v[98:101], v[144:147], v[176:179], v[98:101]
	v_mfma_f32_16x16x32_bf16 v[126:129], v[138:141], v[156:159], v[126:129]
	v_mfma_f32_16x16x32_bf16 v[122:125], v[148:151], v[156:159], v[122:125]
	v_mfma_f32_16x16x32_bf16 v[118:121], v[138:141], v[164:167], v[118:121]
	v_mfma_f32_16x16x32_bf16 v[114:117], v[148:151], v[164:167], v[114:117]
	v_mfma_f32_16x16x32_bf16 v[110:113], v[138:141], v[172:175], v[110:113]
	v_mfma_f32_16x16x32_bf16 v[106:109], v[148:151], v[172:175], v[106:109]
	v_mfma_f32_16x16x32_bf16 v[102:105], v[138:141], v[180:183], v[102:105]
	v_mfma_f32_16x16x32_bf16 v[98:101], v[148:151], v[180:183], v[98:101]
	s_setprio 0
	v_add_u32_e32 v192, 0x14000, v143
	s_barrier
	ds_read_b128 v[130:133], v192
	ds_read_b128 v[184:187], v192 offset:1024
	ds_read_b128 v[188:191], v192 offset:2048
	ds_read_b128 v[192:195], v192 offset:3072
	s_barrier
	s_waitcnt lgkmcnt(0)
	s_setprio 1
	s_waitcnt lgkmcnt(0)
	v_mfma_f32_16x16x32_bf16 v[94:97], v[130:133], v[152:155], v[94:97]
	v_mfma_f32_16x16x32_bf16 v[90:93], v[188:191], v[152:155], v[90:93]
	v_mfma_f32_16x16x32_bf16 v[78:81], v[130:133], v[160:163], v[78:81]
	v_mfma_f32_16x16x32_bf16 v[94:97], v[184:187], v[156:159], v[94:97]
	v_mfma_f32_16x16x32_bf16 v[90:93], v[192:195], v[156:159], v[90:93]
	v_mfma_f32_16x16x32_bf16 v[78:81], v[184:187], v[164:167], v[78:81]
	v_mfma_f32_16x16x32_bf16 v[62:65], v[188:191], v[160:163], v[62:65]
	v_mfma_f32_16x16x32_bf16 v[58:61], v[130:133], v[168:171], v[58:61]
	v_mfma_f32_16x16x32_bf16 v[54:57], v[188:191], v[168:171], v[54:57]
	v_mfma_f32_16x16x32_bf16 v[50:53], v[130:133], v[176:179], v[50:53]
	v_mfma_f32_16x16x32_bf16 v[46:49], v[188:191], v[176:179], v[46:49]
	v_mfma_f32_16x16x32_bf16 v[62:65], v[192:195], v[164:167], v[62:65]
	v_mfma_f32_16x16x32_bf16 v[58:61], v[184:187], v[172:175], v[58:61]
	v_mfma_f32_16x16x32_bf16 v[54:57], v[192:195], v[172:175], v[54:57]
	v_mfma_f32_16x16x32_bf16 v[50:53], v[184:187], v[180:183], v[50:53]
	v_mfma_f32_16x16x32_bf16 v[46:49], v[192:195], v[180:183], v[46:49]
	s_setprio 0
	s_barrier
	ds_read_b128 v[152:155], v142 offset:16384
	ds_read_b128 v[156:159], v142 offset:17408
	ds_read_b128 v[160:163], v142 offset:18432
	ds_read_b128 v[164:167], v142 offset:19456
	ds_read_b128 v[168:171], v142 offset:20480
	ds_read_b128 v[172:175], v142 offset:21504
	ds_read_b128 v[176:179], v142 offset:22528
	ds_read_b128 v[180:183], v142 offset:23552
	s_waitcnt vmcnt(4)
	s_barrier
	s_waitcnt lgkmcnt(0)
	s_setprio 1
	s_waitcnt lgkmcnt(0)
	v_mfma_f32_16x16x32_bf16 v[42:45], v[134:137], v[152:155], v[42:45]
	v_mfma_f32_16x16x32_bf16 v[38:41], v[144:147], v[152:155], v[38:41]
	v_mfma_f32_16x16x32_bf16 v[34:37], v[134:137], v[160:163], v[34:37]
	v_mfma_f32_16x16x32_bf16 v[30:33], v[144:147], v[160:163], v[30:33]
	v_mfma_f32_16x16x32_bf16 v[26:29], v[134:137], v[168:171], v[26:29]
	v_mfma_f32_16x16x32_bf16 v[22:25], v[144:147], v[168:171], v[22:25]
	v_mfma_f32_16x16x32_bf16 v[18:21], v[134:137], v[176:179], v[18:21]
	v_mfma_f32_16x16x32_bf16 v[14:17], v[144:147], v[176:179], v[14:17]
	v_mfma_f32_16x16x32_bf16 v[42:45], v[138:141], v[156:159], v[42:45]
	v_mfma_f32_16x16x32_bf16 v[38:41], v[148:151], v[156:159], v[38:41]
	v_mfma_f32_16x16x32_bf16 v[34:37], v[138:141], v[164:167], v[34:37]
	v_mfma_f32_16x16x32_bf16 v[30:33], v[148:151], v[164:167], v[30:33]
	v_mfma_f32_16x16x32_bf16 v[26:29], v[138:141], v[172:175], v[26:29]
	v_mfma_f32_16x16x32_bf16 v[22:25], v[148:151], v[172:175], v[22:25]
	v_mfma_f32_16x16x32_bf16 v[18:21], v[138:141], v[180:183], v[18:21]
	v_mfma_f32_16x16x32_bf16 v[14:17], v[148:151], v[180:183], v[14:17]
	s_setprio 0
	s_setprio 1
	v_mfma_f32_16x16x32_bf16 v[70:73], v[130:133], v[168:171], v[70:73]
	v_mfma_f32_16x16x32_bf16 v[198:201], v[184:187], v[172:175], v[70:73]
	v_mfma_f32_16x16x32_bf16 v[70:73], v[188:191], v[168:171], v[74:77]
	v_mfma_f32_16x16x32_bf16 v[66:69], v[188:191], v[160:163], v[66:69]
	v_mfma_f32_16x16x32_bf16 v[74:77], v[192:195], v[172:175], v[70:73]
	v_mfma_f32_16x16x32_bf16 v[70:73], v[130:133], v[176:179], v[82:85]
	v_mfma_f32_16x16x32_bf16 v[10:13], v[130:133], v[152:155], v[10:13]
	v_mfma_f32_16x16x32_bf16 v[6:9], v[188:191], v[152:155], v[6:9]
	v_mfma_f32_16x16x32_bf16 v[2:5], v[130:133], v[160:163], v[2:5]
	v_mfma_f32_16x16x32_bf16 v[66:69], v[192:195], v[164:167], v[66:69]
	v_mfma_f32_16x16x32_bf16 v[202:205], v[184:187], v[180:183], v[70:73]
	v_mfma_f32_16x16x32_bf16 v[70:73], v[188:191], v[176:179], v[86:89]
	v_mfma_f32_16x16x32_bf16 v[10:13], v[184:187], v[156:159], v[10:13]
	v_mfma_f32_16x16x32_bf16 v[6:9], v[192:195], v[156:159], v[6:9]
	v_mfma_f32_16x16x32_bf16 v[2:5], v[184:187], v[164:167], v[2:5]
	v_mfma_f32_16x16x32_bf16 v[206:209], v[192:195], v[180:183], v[70:73]
	s_setprio 0
	v_add_u32_e32 v86, 0x18000, v143
	s_barrier
	s_nop 0
	ds_read_b128 v[70:73], v86
	ds_read_b128 v[82:85], v86 offset:1024
	ds_read_b128 v[134:137], v86 offset:2048
	ds_read_b128 v[210:213], v86 offset:3072
	ds_read_b128 v[86:89], v142 offset:32768
	ds_read_b128 v[130:133], v142 offset:33792
	ds_read_b128 v[138:141], v142 offset:34816
	ds_read_b128 v[154:157], v142 offset:35840
	ds_read_b128 v[214:217], v142 offset:36864
	ds_read_b128 v[218:221], v142 offset:37888
	ds_read_b128 v[226:229], v142 offset:38912
	ds_read_b128 v[230:233], v142 offset:39936
	s_waitcnt vmcnt(2)
	s_barrier
	s_waitcnt lgkmcnt(0)
	s_setprio 1
	s_waitcnt lgkmcnt(0)
	v_mfma_f32_16x16x32_bf16 v[126:129], v[70:73], v[86:89], v[126:129]
	v_mfma_f32_16x16x32_bf16 v[122:125], v[134:137], v[86:89], v[122:125]
	v_mfma_f32_16x16x32_bf16 v[118:121], v[70:73], v[138:141], v[118:121]
	v_mfma_f32_16x16x32_bf16 v[114:117], v[134:137], v[138:141], v[114:117]
	v_mfma_f32_16x16x32_bf16 v[110:113], v[70:73], v[214:217], v[110:113]
	v_mfma_f32_16x16x32_bf16 v[106:109], v[134:137], v[214:217], v[106:109]
	v_mfma_f32_16x16x32_bf16 v[102:105], v[70:73], v[226:229], v[102:105]
	v_mfma_f32_16x16x32_bf16 v[98:101], v[134:137], v[226:229], v[98:101]
	v_mfma_f32_16x16x32_bf16 v[182:185], v[82:85], v[130:133], v[126:129]
	v_mfma_f32_16x16x32_bf16 v[178:181], v[210:213], v[130:133], v[122:125]
	v_mfma_f32_16x16x32_bf16 v[166:169], v[82:85], v[154:157], v[118:121]
	v_mfma_f32_16x16x32_bf16 v[162:165], v[210:213], v[154:157], v[114:117]
	v_mfma_f32_16x16x32_bf16 v[150:153], v[82:85], v[218:221], v[110:113]
	v_mfma_f32_16x16x32_bf16 v[146:149], v[210:213], v[218:221], v[106:109]
	v_mfma_f32_16x16x32_bf16 v[122:125], v[82:85], v[230:233], v[102:105]
	v_mfma_f32_16x16x32_bf16 v[114:117], v[210:213], v[230:233], v[98:101]
	s_setprio 0
	s_nop 1
	v_add_u32_e32 v98, 0x1c000, v143
	s_barrier
	ds_read_b128 v[234:237], v98
	ds_read_b128 v[238:241], v98 offset:1024
	ds_read_b128 v[242:245], v98 offset:2048
	ds_read_b128 v[246:249], v98 offset:3072
	s_waitcnt vmcnt(0)
	s_barrier
	s_waitcnt lgkmcnt(0)
	s_setprio 1
	s_waitcnt lgkmcnt(0)
	v_mfma_f32_16x16x32_bf16 v[94:97], v[234:237], v[86:89], v[94:97]
	v_mfma_f32_16x16x32_bf16 v[86:89], v[242:245], v[86:89], v[90:93]
	v_mfma_f32_16x16x32_bf16 v[78:81], v[234:237], v[138:141], v[78:81]
	v_mfma_f32_16x16x32_bf16 v[62:65], v[242:245], v[138:141], v[62:65]
	v_mfma_f32_16x16x32_bf16 v[58:61], v[234:237], v[214:217], v[58:61]
	v_mfma_f32_16x16x32_bf16 v[54:57], v[242:245], v[214:217], v[54:57]
	v_mfma_f32_16x16x32_bf16 v[50:53], v[234:237], v[226:229], v[50:53]
	v_mfma_f32_16x16x32_bf16 v[46:49], v[242:245], v[226:229], v[46:49]
	v_mfma_f32_16x16x32_bf16 v[190:193], v[238:241], v[130:133], v[94:97]
	v_mfma_f32_16x16x32_bf16 v[186:189], v[246:249], v[130:133], v[86:89]
	v_mfma_f32_16x16x32_bf16 v[174:177], v[238:241], v[154:157], v[78:81]
	v_mfma_f32_16x16x32_bf16 v[170:173], v[246:249], v[154:157], v[62:65]
	v_mfma_f32_16x16x32_bf16 v[158:161], v[238:241], v[218:221], v[58:61]
	v_mfma_f32_16x16x32_bf16 v[154:157], v[246:249], v[218:221], v[54:57]
	v_mfma_f32_16x16x32_bf16 v[138:141], v[238:241], v[230:233], v[50:53]
	v_mfma_f32_16x16x32_bf16 v[130:133], v[246:249], v[230:233], v[46:49]
	s_setprio 0
	s_barrier
	s_nop 0
	ds_read_b128 v[46:49], v142 offset:49152
	ds_read_b128 v[50:53], v142 offset:50176
	ds_read_b128 v[54:57], v142 offset:51200
	ds_read_b128 v[58:61], v142 offset:52224
	ds_read_b128 v[62:65], v142 offset:53248
	ds_read_b128 v[214:217], v142 offset:54272
	ds_read_b128 v[218:221], v142 offset:55296
	ds_read_b128 v[226:229], v142 offset:56320
	s_barrier
	s_waitcnt lgkmcnt(0)
	s_setprio 1
	s_waitcnt lgkmcnt(0)
	v_mfma_f32_16x16x32_bf16 v[42:45], v[70:73], v[46:49], v[42:45]
	v_mfma_f32_16x16x32_bf16 v[38:41], v[134:137], v[46:49], v[38:41]
	v_mfma_f32_16x16x32_bf16 v[34:37], v[70:73], v[54:57], v[34:37]
	v_mfma_f32_16x16x32_bf16 v[30:33], v[134:137], v[54:57], v[30:33]
	v_mfma_f32_16x16x32_bf16 v[26:29], v[70:73], v[62:65], v[26:29]
	v_mfma_f32_16x16x32_bf16 v[22:25], v[134:137], v[62:65], v[22:25]
	v_mfma_f32_16x16x32_bf16 v[18:21], v[70:73], v[218:221], v[18:21]
	v_mfma_f32_16x16x32_bf16 v[14:17], v[134:137], v[218:221], v[14:17]
	v_mfma_f32_16x16x32_bf16 v[142:145], v[82:85], v[50:53], v[42:45]
	v_mfma_f32_16x16x32_bf16 v[126:129], v[210:213], v[50:53], v[38:41]
	v_mfma_f32_16x16x32_bf16 v[110:113], v[82:85], v[58:61], v[34:37]
	v_mfma_f32_16x16x32_bf16 v[102:105], v[210:213], v[58:61], v[30:33]
	v_mfma_f32_16x16x32_bf16 v[94:97], v[82:85], v[214:217], v[26:29]
	v_mfma_f32_16x16x32_bf16 v[86:89], v[210:213], v[214:217], v[22:25]
	v_mfma_f32_16x16x32_bf16 v[78:81], v[82:85], v[226:229], v[18:21]
	v_mfma_f32_16x16x32_bf16 v[70:73], v[210:213], v[226:229], v[14:17]
	s_setprio 0
	s_setprio 1
	v_mfma_f32_16x16x32_bf16 v[2:5], v[234:237], v[54:57], v[2:5]
	v_mfma_f32_16x16x32_bf16 v[106:109], v[238:241], v[58:61], v[2:5]
	v_mfma_f32_16x16x32_bf16 v[2:5], v[242:245], v[54:57], v[66:69]
	v_mfma_f32_16x16x32_bf16 v[98:101], v[246:249], v[58:61], v[2:5]
	v_mfma_f32_16x16x32_bf16 v[2:5], v[234:237], v[62:65], v[198:201]
	v_mfma_f32_16x16x32_bf16 v[90:93], v[238:241], v[214:217], v[2:5]
	v_mfma_f32_16x16x32_bf16 v[2:5], v[242:245], v[62:65], v[74:77]
	v_mfma_f32_16x16x32_bf16 v[82:85], v[246:249], v[214:217], v[2:5]
	v_mfma_f32_16x16x32_bf16 v[2:5], v[234:237], v[218:221], v[202:205]
	v_mfma_f32_16x16x32_bf16 v[10:13], v[234:237], v[46:49], v[10:13]
	v_mfma_f32_16x16x32_bf16 v[6:9], v[242:245], v[46:49], v[6:9]
	v_mfma_f32_16x16x32_bf16 v[74:77], v[238:241], v[226:229], v[2:5]
	v_mfma_f32_16x16x32_bf16 v[2:5], v[242:245], v[218:221], v[206:209]
	v_mfma_f32_16x16x32_bf16 v[134:137], v[238:241], v[50:53], v[10:13]
	v_mfma_f32_16x16x32_bf16 v[118:121], v[246:249], v[50:53], v[6:9]
	v_mfma_f32_16x16x32_bf16 v[66:69], v[246:249], v[226:229], v[2:5]
	s_setprio 0
	s_cmpk_lt_u32 s33, 0x100
	s_barrier
	s_cbranch_scc0 .LBB0_164
	s_barrier

.LBB0_195:
	v_and_b32_e32 v17, 15, v16
	v_and_b32_e32 v18, 48, v16
	v_lshlrev_b32_e32 v16, 2, v16
	v_lshlrev_b32_e32 v17, 6, v17
	v_and_b32_e32 v16, 32, v16
	s_lshl_b32 s37, s37, 12
	v_or_b32_e32 v19, v17, v18
	v_bitop3_b32 v17, v17, v16, v18 bitop3:0x36
	s_lshl_b32 s36, s36, 13
	s_and_b32 s37, s37, 0x3000
	s_add_i32 m0, s69, 0x18000
	v_lshl_add_u64 v[8:9], v[8:9], 0, s[48:49]
	v_bitop3_b32 v16, v19, s36, v16 bitop3:0xde
	v_or_b32_e32 v143, s37, v17
	s_waitcnt vmcnt(4)
	s_barrier
	global_load_lds_dwordx4 v[8:9], off
	v_lshl_add_u64 v[6:7], v[6:7], 0, s[48:49]
	s_add_i32 m0, s69, 0x1a000
	s_add_i32 s36, s69, 0x8000
	s_add_i32 s37, s69, 0xa000
	global_load_lds_dwordx4 v[6:7], off
	v_lshl_add_u64 v[4:5], v[4:5], 0, s[48:49]
	s_mov_b32 m0, s36
	s_add_u32 s76, vcc_lo, 0x40080
	global_load_lds_dwordx4 v[4:5], off
	v_lshl_add_u64 v[2:3], v[2:3], 0, s[48:49]
	s_mov_b32 m0, s37
	s_addc_u32 s77, vcc_hi, 0
	global_load_lds_dwordx4 v[2:3], off
	s_add_i32 m0, s69, 0x1c000
	v_lshl_add_u64 v[2:3], s[76:77], 0, v[130:131]
	global_load_lds_dwordx4 v[2:3], off
	v_lshl_add_u64 v[2:3], s[76:77], 0, v[132:133]
	s_add_i32 m0, s69, 0x1e000
	v_readlane_b32 s18, v253, 1
	global_load_lds_dwordx4 v[2:3], off
	v_lshlrev_b32_e32 v2, 14, v10
	v_and_b32_e32 v2, 0xffff8000, v2
	v_readlane_b32 s19, v253, 2
	s_add_u32 s44, s18, s44
	v_lshlrev_b32_e32 v4, 14, v11
	v_lshl_add_u32 v2, v12, 11, v2
	v_and_b32_e32 v3, 1, v10
	s_addc_u32 s45, s19, s45
	v_and_b32_e32 v4, 0xffff8000, v4
	v_lshl_or_b32 v2, v3, 6, v2
	v_lshl_add_u32 v4, v14, 11, v4
	v_and_b32_e32 v5, 1, v11
	s_add_u32 s40, s18, s40
	s_waitcnt vmcnt(6)
	v_lshl_add_u32 v2, v13, 1, v2
	v_mov_b32_e32 v3, v196
	v_lshl_or_b32 v4, v5, 6, v4
	s_addc_u32 s41, s19, s41
	v_lshl_add_u64 v[134:135], s[44:45], 0, v[2:3]
	v_lshl_add_u32 v4, v15, 1, v4
	v_mov_b32_e32 v5, v196
	v_lshl_add_u64 v[138:139], s[40:41], 0, v[2:3]
	v_mov_b32_e32 v2, 0
	v_lshl_add_u64 v[136:137], s[44:45], 0, v[4:5]
	v_lshl_add_u64 v[140:141], s[40:41], 0, v[4:5]
	s_mov_b32 s40, -2
	v_add_u32_e32 v142, 0, v16
	v_mov_b32_e32 v3, v2
	v_mov_b32_e32 v4, v2
	v_mov_b32_e32 v5, v2
	v_mov_b32_e32 v6, v2
	v_mov_b32_e32 v7, v2
	v_mov_b32_e32 v8, v2
	v_mov_b32_e32 v9, v2
	v_mov_b32_e32 v10, v2
	v_mov_b32_e32 v11, v2
	v_mov_b32_e32 v12, v2
	v_mov_b32_e32 v13, v2
	v_mov_b32_e32 v14, v2
	v_mov_b32_e32 v15, v2
	v_mov_b32_e32 v16, v2
	v_mov_b32_e32 v17, v2
	v_mov_b32_e32 v18, v2
	v_mov_b32_e32 v19, v2
	v_mov_b32_e32 v20, v2
	v_mov_b32_e32 v21, v2
	v_mov_b32_e32 v22, v2
	v_mov_b32_e32 v23, v2
	v_mov_b32_e32 v24, v2
	v_mov_b32_e32 v25, v2
	v_mov_b32_e32 v26, v2
	v_mov_b32_e32 v27, v2
	v_mov_b32_e32 v28, v2
	v_mov_b32_e32 v29, v2
	v_mov_b32_e32 v30, v2
	v_mov_b32_e32 v31, v2
	v_mov_b32_e32 v32, v2
	v_mov_b32_e32 v33, v2
	v_mov_b32_e32 v34, v2
	v_mov_b32_e32 v35, v2
	v_mov_b32_e32 v36, v2
	v_mov_b32_e32 v37, v2
	v_mov_b32_e32 v38, v2
	v_mov_b32_e32 v39, v2
	v_mov_b32_e32 v40, v2
	v_mov_b32_e32 v41, v2
	v_mov_b32_e32 v42, v2
	v_mov_b32_e32 v43, v2
	v_mov_b32_e32 v44, v2
	v_mov_b32_e32 v45, v2
	v_mov_b32_e32 v46, v2
	v_mov_b32_e32 v47, v2
	v_mov_b32_e32 v48, v2
	v_mov_b32_e32 v49, v2
	v_mov_b32_e32 v50, v2
	v_mov_b32_e32 v51, v2
	v_mov_b32_e32 v52, v2
	v_mov_b32_e32 v53, v2
	v_mov_b32_e32 v54, v2
	v_mov_b32_e32 v55, v2
	v_mov_b32_e32 v56, v2
	v_mov_b32_e32 v57, v2
	v_mov_b32_e32 v58, v2
	v_mov_b32_e32 v59, v2
	v_mov_b32_e32 v60, v2
	v_mov_b32_e32 v61, v2
	v_mov_b32_e32 v62, v2
	v_mov_b32_e32 v63, v2
	v_mov_b32_e32 v64, v2
	v_mov_b32_e32 v65, v2
	v_mov_b32_e32 v66, v2
	v_mov_b32_e32 v67, v2
	v_mov_b32_e32 v68, v2
	v_mov_b32_e32 v69, v2
	v_mov_b32_e32 v70, v2
	v_mov_b32_e32 v71, v2
	v_mov_b32_e32 v72, v2
	v_mov_b32_e32 v73, v2
	v_mov_b32_e32 v78, v2
	v_mov_b32_e32 v79, v2
	v_mov_b32_e32 v80, v2
	v_mov_b32_e32 v81, v2
	v_mov_b32_e32 v82, v2
	v_mov_b32_e32 v83, v2
	v_mov_b32_e32 v84, v2
	v_mov_b32_e32 v85, v2
	v_mov_b32_e32 v86, v2
	v_mov_b32_e32 v87, v2
	v_mov_b32_e32 v88, v2
	v_mov_b32_e32 v89, v2
	v_mov_b32_e32 v90, v2
	v_mov_b32_e32 v91, v2
	v_mov_b32_e32 v92, v2
	v_mov_b32_e32 v93, v2
	v_mov_b32_e32 v94, v2
	v_mov_b32_e32 v95, v2
	v_mov_b32_e32 v96, v2
	v_mov_b32_e32 v97, v2
	v_mov_b32_e32 v98, v2
	v_mov_b32_e32 v99, v2
	v_mov_b32_e32 v100, v2
	v_mov_b32_e32 v101, v2
	v_mov_b32_e32 v102, v2
	v_mov_b32_e32 v103, v2
	v_mov_b32_e32 v104, v2
	v_mov_b32_e32 v105, v2
	v_mov_b32_e32 v106, v2
	v_mov_b32_e32 v107, v2
	v_mov_b32_e32 v108, v2
	v_mov_b32_e32 v109, v2
	v_mov_b32_e32 v110, v2
	v_mov_b32_e32 v111, v2
	v_mov_b32_e32 v112, v2
	v_mov_b32_e32 v113, v2
	v_mov_b32_e32 v114, v2
	v_mov_b32_e32 v115, v2
	v_mov_b32_e32 v116, v2
	v_mov_b32_e32 v117, v2
	v_mov_b32_e32 v118, v2
	v_mov_b32_e32 v119, v2
	v_mov_b32_e32 v120, v2
	v_mov_b32_e32 v121, v2
	v_mov_b32_e32 v122, v2
	v_mov_b32_e32 v123, v2
	v_mov_b32_e32 v124, v2
	v_mov_b32_e32 v125, v2
	v_mov_b32_e32 v126, v2
	v_mov_b32_e32 v127, v2
	v_mov_b32_e32 v128, v2
	v_mov_b32_e32 v129, v2
	v_mov_b32_e32 v74, v2
	v_mov_b32_e32 v75, v2
	v_mov_b32_e32 v76, v2
	v_mov_b32_e32 v77, v2
	s_barrier
	v_add_u32_e32 v156, 0x10000, v143
	ds_read_b128 v[144:147], v156
	ds_read_b128 v[148:151], v156 offset:1024
	ds_read_b128 v[152:155], v156 offset:2048
	ds_read_b128 v[156:159], v156 offset:3072
.LBB0_196:
	s_add_i32 s45, 0, 0x10000
	v_lshl_add_u64 v[210:211], v[138:139], 0, s[14:15]
	s_add_i32 s44, s69, 0xc000
	v_lshl_add_u64 v[192:193], v[210:211], 0, s[94:95]
	s_mov_b32 m0, s44
	v_lshl_add_u64 v[212:213], v[140:141], 0, s[14:15]
	s_add_i32 s41, s69, 0xe000
	ds_read_b128 v[160:163], v142
	ds_read_b128 v[164:167], v142 offset:1024
	ds_read_b128 v[168:171], v142 offset:2048
	ds_read_b128 v[172:175], v142 offset:3072
	ds_read_b128 v[176:179], v142 offset:4096
	ds_read_b128 v[180:183], v142 offset:5120
	ds_read_b128 v[184:187], v142 offset:6144
	ds_read_b128 v[188:191], v142 offset:7168
	global_load_lds_dwordx4 v[192:193], off
	v_lshl_add_u64 v[192:193], v[212:213], 0, s[94:95]
	s_mov_b32 m0, s41
	s_nop 0
	global_load_lds_dwordx4 v[192:193], off
	s_waitcnt lgkmcnt(8)
	s_barrier
	s_waitcnt lgkmcnt(0)
	s_setprio 1
	s_waitcnt lgkmcnt(0)
	v_mfma_f32_16x16x32_bf16 v[126:129], v[144:147], v[160:163], v[126:129]
	v_mfma_f32_16x16x32_bf16 v[122:125], v[152:155], v[160:163], v[122:125]
	v_mfma_f32_16x16x32_bf16 v[118:121], v[144:147], v[168:171], v[118:121]
	v_mfma_f32_16x16x32_bf16 v[114:117], v[152:155], v[168:171], v[114:117]
	v_mfma_f32_16x16x32_bf16 v[110:113], v[144:147], v[176:179], v[110:113]
	v_mfma_f32_16x16x32_bf16 v[106:109], v[152:155], v[176:179], v[106:109]
	v_mfma_f32_16x16x32_bf16 v[102:105], v[144:147], v[184:187], v[102:105]
	v_mfma_f32_16x16x32_bf16 v[98:101], v[152:155], v[184:187], v[98:101]
	v_mfma_f32_16x16x32_bf16 v[126:129], v[148:151], v[164:167], v[126:129]
	v_mfma_f32_16x16x32_bf16 v[122:125], v[156:159], v[164:167], v[122:125]
	v_mfma_f32_16x16x32_bf16 v[118:121], v[148:151], v[172:175], v[118:121]
	v_mfma_f32_16x16x32_bf16 v[114:117], v[156:159], v[172:175], v[114:117]
	v_mfma_f32_16x16x32_bf16 v[110:113], v[148:151], v[180:183], v[110:113]
	v_mfma_f32_16x16x32_bf16 v[106:109], v[156:159], v[180:183], v[106:109]
	v_mfma_f32_16x16x32_bf16 v[102:105], v[148:151], v[188:191], v[102:105]
	v_mfma_f32_16x16x32_bf16 v[98:101], v[156:159], v[188:191], v[98:101]
	s_setprio 0
	s_barrier
	s_add_i32 s75, 0, 0x14000
	v_lshl_add_u64 v[214:215], v[134:135], 0, s[14:15]
	s_add_i32 s45, s45, s68
	v_add_u32_e32 v197, s75, v143
	v_lshl_add_u64 v[216:217], v[214:215], 0, s[96:97]
	s_mov_b32 m0, s45
	ds_read_b128 v[192:195], v197
	ds_read_b128 v[198:201], v197 offset:1024
	ds_read_b128 v[202:205], v197 offset:2048
	ds_read_b128 v[206:209], v197 offset:3072
	global_load_lds_dwordx4 v[216:217], off
	v_lshl_add_u64 v[216:217], v[136:137], 0, s[14:15]
	v_lshl_add_u64 v[218:219], v[216:217], 0, s[96:97]
	s_add_i32 m0, s45, 0x2000
	s_nop 0
	global_load_lds_dwordx4 v[218:219], off
	s_barrier
	s_waitcnt lgkmcnt(0)
	s_setprio 1
	s_waitcnt lgkmcnt(0)
	v_mfma_f32_16x16x32_bf16 v[94:97], v[192:195], v[160:163], v[94:97]
	v_mfma_f32_16x16x32_bf16 v[90:93], v[202:205], v[160:163], v[90:93]
	v_mfma_f32_16x16x32_bf16 v[86:89], v[192:195], v[168:171], v[86:89]
	v_mfma_f32_16x16x32_bf16 v[82:85], v[202:205], v[168:171], v[82:85]
	v_mfma_f32_16x16x32_bf16 v[78:81], v[192:195], v[176:179], v[78:81]
	v_mfma_f32_16x16x32_bf16 v[70:73], v[202:205], v[176:179], v[70:73]
	v_mfma_f32_16x16x32_bf16 v[66:69], v[192:195], v[184:187], v[66:69]
	v_mfma_f32_16x16x32_bf16 v[62:65], v[202:205], v[184:187], v[62:65]
	v_mfma_f32_16x16x32_bf16 v[94:97], v[198:201], v[164:167], v[94:97]
	v_mfma_f32_16x16x32_bf16 v[90:93], v[206:209], v[164:167], v[90:93]
	v_mfma_f32_16x16x32_bf16 v[86:89], v[198:201], v[172:175], v[86:89]
	v_mfma_f32_16x16x32_bf16 v[82:85], v[206:209], v[172:175], v[82:85]
	v_mfma_f32_16x16x32_bf16 v[78:81], v[198:201], v[180:183], v[78:81]
	v_mfma_f32_16x16x32_bf16 v[70:73], v[206:209], v[180:183], v[70:73]
	v_mfma_f32_16x16x32_bf16 v[66:69], v[198:201], v[188:191], v[66:69]
	v_mfma_f32_16x16x32_bf16 v[62:65], v[206:209], v[188:191], v[62:65]
	s_setprio 0
	s_mov_b32 m0, s69
	v_lshl_add_u64 v[218:219], v[210:211], 0, s[38:39]
	s_barrier
	ds_read_b128 v[160:163], v142 offset:16384
	ds_read_b128 v[164:167], v142 offset:17408
	ds_read_b128 v[168:171], v142 offset:18432
	ds_read_b128 v[172:175], v142 offset:19456
	ds_read_b128 v[176:179], v142 offset:20480
	ds_read_b128 v[180:183], v142 offset:21504
	ds_read_b128 v[184:187], v142 offset:22528
	ds_read_b128 v[188:191], v142 offset:23552
	global_load_lds_dwordx4 v[218:219], off
	v_lshl_add_u64 v[218:219], v[212:213], 0, s[38:39]
	s_mov_b32 m0, s73
	s_nop 0
	global_load_lds_dwordx4 v[218:219], off
	s_waitcnt vmcnt(10)
	s_barrier
	s_waitcnt lgkmcnt(0)
	s_setprio 1
	s_waitcnt lgkmcnt(0)
	v_mfma_f32_16x16x32_bf16 v[58:61], v[144:147], v[160:163], v[58:61]
	v_mfma_f32_16x16x32_bf16 v[54:57], v[152:155], v[160:163], v[54:57]
	v_mfma_f32_16x16x32_bf16 v[50:53], v[144:147], v[168:171], v[50:53]
	v_mfma_f32_16x16x32_bf16 v[46:49], v[152:155], v[168:171], v[46:49]
	v_mfma_f32_16x16x32_bf16 v[42:45], v[144:147], v[176:179], v[42:45]
	v_mfma_f32_16x16x32_bf16 v[38:41], v[152:155], v[176:179], v[38:41]
	v_mfma_f32_16x16x32_bf16 v[34:37], v[144:147], v[184:187], v[34:37]
	v_mfma_f32_16x16x32_bf16 v[30:33], v[152:155], v[184:187], v[30:33]
	v_mfma_f32_16x16x32_bf16 v[58:61], v[148:151], v[164:167], v[58:61]
	v_mfma_f32_16x16x32_bf16 v[54:57], v[156:159], v[164:167], v[54:57]
	v_mfma_f32_16x16x32_bf16 v[50:53], v[148:151], v[172:175], v[50:53]
	v_mfma_f32_16x16x32_bf16 v[46:49], v[156:159], v[172:175], v[46:49]
	v_mfma_f32_16x16x32_bf16 v[42:45], v[148:151], v[180:183], v[42:45]
	v_mfma_f32_16x16x32_bf16 v[38:41], v[156:159], v[180:183], v[38:41]
	v_mfma_f32_16x16x32_bf16 v[34:37], v[148:151], v[188:191], v[34:37]
	v_mfma_f32_16x16x32_bf16 v[30:33], v[156:159], v[188:191], v[30:33]
	s_setprio 0
	s_barrier
	s_add_i32 s45, s75, s68
	v_lshl_add_u64 v[144:145], v[214:215], 0, s[50:51]
	s_mov_b32 m0, s45
	s_nop 0
	global_load_lds_dwordx4 v[144:145], off
	v_lshl_add_u64 v[144:145], v[216:217], 0, s[50:51]
	s_add_i32 m0, s45, 0x2000
	s_nop 0
	global_load_lds_dwordx4 v[144:145], off
	v_add_u32_e32 v156, 0x18000, v143
	ds_read_b128 v[144:147], v156
	ds_read_b128 v[148:151], v156 offset:1024
	ds_read_b128 v[152:155], v156 offset:2048
	ds_read_b128 v[156:159], v156 offset:3072
	s_waitcnt vmcnt(6)
	s_barrier
	s_setprio 1
	v_mfma_f32_16x16x32_bf16 v[26:29], v[192:195], v[160:163], v[26:29]
	v_mfma_f32_16x16x32_bf16 v[22:25], v[202:205], v[160:163], v[22:25]
	v_mfma_f32_16x16x32_bf16 v[18:21], v[192:195], v[168:171], v[18:21]
	v_mfma_f32_16x16x32_bf16 v[14:17], v[202:205], v[168:171], v[14:17]
	v_mfma_f32_16x16x32_bf16 v[10:13], v[192:195], v[176:179], v[10:13]
	v_mfma_f32_16x16x32_bf16 v[6:9], v[202:205], v[176:179], v[6:9]
	v_mfma_f32_16x16x32_bf16 v[2:5], v[192:195], v[184:187], v[2:5]
	v_mfma_f32_16x16x32_bf16 v[74:77], v[202:205], v[184:187], v[74:77]
	v_mfma_f32_16x16x32_bf16 v[26:29], v[198:201], v[164:167], v[26:29]
	v_mfma_f32_16x16x32_bf16 v[22:25], v[206:209], v[164:167], v[22:25]
	v_mfma_f32_16x16x32_bf16 v[18:21], v[198:201], v[172:175], v[18:21]
	v_mfma_f32_16x16x32_bf16 v[14:17], v[206:209], v[172:175], v[14:17]
	v_mfma_f32_16x16x32_bf16 v[10:13], v[198:201], v[180:183], v[10:13]
	v_mfma_f32_16x16x32_bf16 v[6:9], v[206:209], v[180:183], v[6:9]
	v_mfma_f32_16x16x32_bf16 v[2:5], v[198:201], v[188:191], v[2:5]
	v_mfma_f32_16x16x32_bf16 v[74:77], v[206:209], v[188:191], v[74:77]
	s_setprio 0
	s_add_i32 s45, 0, 0x18000
	s_barrier
	s_mov_b32 m0, s78
	v_lshl_add_u64 v[192:193], v[210:211], 0, s[4:5]
	ds_read_b128 v[160:163], v142 offset:32768
	ds_read_b128 v[164:167], v142 offset:33792
	ds_read_b128 v[168:171], v142 offset:34816
	ds_read_b128 v[172:175], v142 offset:35840
	ds_read_b128 v[176:179], v142 offset:36864
	ds_read_b128 v[180:183], v142 offset:37888
	ds_read_b128 v[184:187], v142 offset:38912
	ds_read_b128 v[188:191], v142 offset:39936
	global_load_lds_dwordx4 v[192:193], off
	v_lshl_add_u64 v[192:193], v[212:213], 0, s[4:5]
	s_mov_b32 m0, s74
	s_nop 0
	global_load_lds_dwordx4 v[192:193], off
	s_waitcnt lgkmcnt(8)
	s_barrier
	s_waitcnt lgkmcnt(0)
	s_setprio 1
	s_waitcnt lgkmcnt(0)
	v_mfma_f32_16x16x32_bf16 v[126:129], v[144:147], v[160:163], v[126:129]
	v_mfma_f32_16x16x32_bf16 v[122:125], v[152:155], v[160:163], v[122:125]
	v_mfma_f32_16x16x32_bf16 v[118:121], v[144:147], v[168:171], v[118:121]
	v_mfma_f32_16x16x32_bf16 v[114:117], v[152:155], v[168:171], v[114:117]
	v_mfma_f32_16x16x32_bf16 v[110:113], v[144:147], v[176:179], v[110:113]
	v_mfma_f32_16x16x32_bf16 v[106:109], v[152:155], v[176:179], v[106:109]
	v_mfma_f32_16x16x32_bf16 v[102:105], v[144:147], v[184:187], v[102:105]
	v_mfma_f32_16x16x32_bf16 v[98:101], v[152:155], v[184:187], v[98:101]
	v_mfma_f32_16x16x32_bf16 v[126:129], v[148:151], v[164:167], v[126:129]
	v_mfma_f32_16x16x32_bf16 v[122:125], v[156:159], v[164:167], v[122:125]
	v_mfma_f32_16x16x32_bf16 v[118:121], v[148:151], v[172:175], v[118:121]
	v_mfma_f32_16x16x32_bf16 v[114:117], v[156:159], v[172:175], v[114:117]
	v_mfma_f32_16x16x32_bf16 v[110:113], v[148:151], v[180:183], v[110:113]
	v_mfma_f32_16x16x32_bf16 v[106:109], v[156:159], v[180:183], v[106:109]
	v_mfma_f32_16x16x32_bf16 v[102:105], v[148:151], v[188:191], v[102:105]
	v_mfma_f32_16x16x32_bf16 v[98:101], v[156:159], v[188:191], v[98:101]
	s_setprio 0
	s_barrier
	s_add_i32 s75, 0, 0x1c000
	s_add_i32 s45, s45, s68
	v_add_u32_e32 v197, s75, v143
	v_lshl_add_u64 v[218:219], v[214:215], 0, s[6:7]
	s_mov_b32 m0, s45
	ds_read_b128 v[192:195], v197
	ds_read_b128 v[198:201], v197 offset:1024
	ds_read_b128 v[202:205], v197 offset:2048
	ds_read_b128 v[206:209], v197 offset:3072
	global_load_lds_dwordx4 v[218:219], off
	v_lshl_add_u64 v[218:219], v[216:217], 0, s[6:7]
	s_add_i32 m0, s45, 0x2000
	s_nop 0
	global_load_lds_dwordx4 v[218:219], off
	s_barrier
	s_waitcnt lgkmcnt(0)
	s_setprio 1
	s_waitcnt lgkmcnt(0)
	v_mfma_f32_16x16x32_bf16 v[94:97], v[192:195], v[160:163], v[94:97]
	v_mfma_f32_16x16x32_bf16 v[90:93], v[202:205], v[160:163], v[90:93]
	v_mfma_f32_16x16x32_bf16 v[86:89], v[192:195], v[168:171], v[86:89]
	v_mfma_f32_16x16x32_bf16 v[82:85], v[202:205], v[168:171], v[82:85]
	v_mfma_f32_16x16x32_bf16 v[78:81], v[192:195], v[176:179], v[78:81]
	v_mfma_f32_16x16x32_bf16 v[70:73], v[202:205], v[176:179], v[70:73]
	v_mfma_f32_16x16x32_bf16 v[66:69], v[192:195], v[184:187], v[66:69]
	v_mfma_f32_16x16x32_bf16 v[62:65], v[202:205], v[184:187], v[62:65]
	v_mfma_f32_16x16x32_bf16 v[94:97], v[198:201], v[164:167], v[94:97]
	v_mfma_f32_16x16x32_bf16 v[90:93], v[206:209], v[164:167], v[90:93]
	v_mfma_f32_16x16x32_bf16 v[86:89], v[198:201], v[172:175], v[86:89]
	v_mfma_f32_16x16x32_bf16 v[82:85], v[206:209], v[172:175], v[82:85]
	v_mfma_f32_16x16x32_bf16 v[78:81], v[198:201], v[180:183], v[78:81]
	v_mfma_f32_16x16x32_bf16 v[70:73], v[206:209], v[180:183], v[70:73]
	v_mfma_f32_16x16x32_bf16 v[66:69], v[198:201], v[188:191], v[66:69]
	v_mfma_f32_16x16x32_bf16 v[62:65], v[206:209], v[188:191], v[62:65]
	s_setprio 0
	s_mov_b32 m0, s36
	v_lshl_add_u64 v[210:211], v[210:211], 0, s[8:9]
	s_barrier
	ds_read_b128 v[160:163], v142 offset:49152
	ds_read_b128 v[164:167], v142 offset:50176
	ds_read_b128 v[168:171], v142 offset:51200
	ds_read_b128 v[172:175], v142 offset:52224
	ds_read_b128 v[176:179], v142 offset:53248
	ds_read_b128 v[180:183], v142 offset:54272
	ds_read_b128 v[184:187], v142 offset:55296
	ds_read_b128 v[188:191], v142 offset:56320
	global_load_lds_dwordx4 v[210:211], off
	v_lshl_add_u64 v[210:211], v[212:213], 0, s[8:9]
	s_mov_b32 m0, s37
	s_nop 0
	global_load_lds_dwordx4 v[210:211], off
	s_waitcnt vmcnt(10)
	s_barrier
	s_waitcnt lgkmcnt(0)
	s_setprio 1
	s_waitcnt lgkmcnt(0)
	v_mfma_f32_16x16x32_bf16 v[58:61], v[144:147], v[160:163], v[58:61]
	v_mfma_f32_16x16x32_bf16 v[54:57], v[152:155], v[160:163], v[54:57]
	v_mfma_f32_16x16x32_bf16 v[50:53], v[144:147], v[168:171], v[50:53]
	v_mfma_f32_16x16x32_bf16 v[46:49], v[152:155], v[168:171], v[46:49]
	v_mfma_f32_16x16x32_bf16 v[42:45], v[144:147], v[176:179], v[42:45]
	v_mfma_f32_16x16x32_bf16 v[38:41], v[152:155], v[176:179], v[38:41]
	v_mfma_f32_16x16x32_bf16 v[34:37], v[144:147], v[184:187], v[34:37]
	v_mfma_f32_16x16x32_bf16 v[30:33], v[152:155], v[184:187], v[30:33]
	v_mfma_f32_16x16x32_bf16 v[58:61], v[148:151], v[164:167], v[58:61]
	v_mfma_f32_16x16x32_bf16 v[54:57], v[156:159], v[164:167], v[54:57]
	v_mfma_f32_16x16x32_bf16 v[50:53], v[148:151], v[172:175], v[50:53]
	v_mfma_f32_16x16x32_bf16 v[46:49], v[156:159], v[172:175], v[46:49]
	v_mfma_f32_16x16x32_bf16 v[42:45], v[148:151], v[180:183], v[42:45]
	v_mfma_f32_16x16x32_bf16 v[38:41], v[156:159], v[180:183], v[38:41]
	v_mfma_f32_16x16x32_bf16 v[34:37], v[148:151], v[188:191], v[34:37]
	v_mfma_f32_16x16x32_bf16 v[30:33], v[156:159], v[188:191], v[30:33]
	s_setprio 0
	s_barrier
	s_add_i32 s45, s75, s68
	v_lshl_add_u64 v[144:145], v[214:215], 0, s[10:11]
	s_mov_b32 m0, s45
	s_nop 0
	global_load_lds_dwordx4 v[144:145], off
	v_lshl_add_u64 v[144:145], v[216:217], 0, s[10:11]
	s_add_i32 m0, s45, 0x2000
	s_nop 0
	global_load_lds_dwordx4 v[144:145], off
	v_add_u32_e32 v156, 0x10000, v143
	ds_read_b128 v[144:147], v156
	ds_read_b128 v[148:151], v156 offset:1024
	ds_read_b128 v[152:155], v156 offset:2048
	ds_read_b128 v[156:159], v156 offset:3072
	s_waitcnt vmcnt(6)
	s_barrier
	s_setprio 1
	v_mfma_f32_16x16x32_bf16 v[26:29], v[192:195], v[160:163], v[26:29]
	v_mfma_f32_16x16x32_bf16 v[22:25], v[202:205], v[160:163], v[22:25]
	v_mfma_f32_16x16x32_bf16 v[18:21], v[192:195], v[168:171], v[18:21]
	v_mfma_f32_16x16x32_bf16 v[14:17], v[202:205], v[168:171], v[14:17]
	v_mfma_f32_16x16x32_bf16 v[10:13], v[192:195], v[176:179], v[10:13]
	v_mfma_f32_16x16x32_bf16 v[6:9], v[202:205], v[176:179], v[6:9]
	v_mfma_f32_16x16x32_bf16 v[2:5], v[192:195], v[184:187], v[2:5]
	v_mfma_f32_16x16x32_bf16 v[74:77], v[202:205], v[184:187], v[74:77]
	v_mfma_f32_16x16x32_bf16 v[26:29], v[198:201], v[164:167], v[26:29]
	v_mfma_f32_16x16x32_bf16 v[22:25], v[206:209], v[164:167], v[22:25]
	v_mfma_f32_16x16x32_bf16 v[18:21], v[198:201], v[172:175], v[18:21]
	v_mfma_f32_16x16x32_bf16 v[14:17], v[206:209], v[172:175], v[14:17]
	v_mfma_f32_16x16x32_bf16 v[10:13], v[198:201], v[180:183], v[10:13]
	v_mfma_f32_16x16x32_bf16 v[6:9], v[206:209], v[180:183], v[6:9]
	v_mfma_f32_16x16x32_bf16 v[2:5], v[198:201], v[188:191], v[2:5]
	v_mfma_f32_16x16x32_bf16 v[74:77], v[206:209], v[188:191], v[74:77]
	s_setprio 0
	s_add_i32 s40, s40, 2
	v_lshl_add_u64 v[134:135], v[134:135], 0, s[98:99]
	v_lshl_add_u64 v[136:137], v[136:137], 0, s[98:99]
	v_lshl_add_u64 v[138:139], v[138:139], 0, s[98:99]
	s_cmp_gt_u32 s40, 11
	v_lshl_add_u64 v[140:141], v[140:141], 0, s[98:99]
	s_barrier
	s_cbranch_scc0 .LBB0_196
	s_waitcnt lgkmcnt(0)
	s_add_u32 s16, s16, 0x40780
	v_add_u32_e32 v143, 0, v143
	s_addc_u32 s17, s17, 0
	s_mov_b32 m0, s44
	v_add_u32_e32 v148, 0x10000, v143
	v_lshl_add_u64 v[130:131], s[16:17], 0, v[130:131]
	ds_read_b128 v[134:137], v148
	ds_read_b128 v[138:141], v148 offset:1024
	ds_read_b128 v[144:147], v148 offset:2048
	ds_read_b128 v[148:151], v148 offset:3072
	ds_read_b128 v[152:155], v142
	ds_read_b128 v[156:159], v142 offset:1024
	ds_read_b128 v[160:163], v142 offset:2048
	ds_read_b128 v[164:167], v142 offset:3072
	ds_read_b128 v[168:171], v142 offset:4096
	ds_read_b128 v[172:175], v142 offset:5120
	ds_read_b128 v[176:179], v142 offset:6144
	ds_read_b128 v[180:183], v142 offset:7168
	global_load_lds_dwordx4 v[130:131], off
	v_lshl_add_u64 v[130:131], s[16:17], 0, v[132:133]
	s_mov_b32 m0, s41
	s_nop 0
	global_load_lds_dwordx4 v[130:131], off
	s_barrier
	s_waitcnt lgkmcnt(0)
	s_setprio 1
	s_waitcnt lgkmcnt(0)
	v_mfma_f32_16x16x32_bf16 v[126:129], v[134:137], v[152:155], v[126:129]
	v_mfma_f32_16x16x32_bf16 v[122:125], v[144:147], v[152:155], v[122:125]
	v_mfma_f32_16x16x32_bf16 v[118:121], v[134:137], v[160:163], v[118:121]
	v_mfma_f32_16x16x32_bf16 v[114:117], v[144:147], v[160:163], v[114:117]
	v_mfma_f32_16x16x32_bf16 v[110:113], v[134:137], v[168:171], v[110:113]
	v_mfma_f32_16x16x32_bf16 v[106:109], v[144:147], v[168:171], v[106:109]
	v_mfma_f32_16x16x32_bf16 v[102:105], v[134:137], v[176:179], v[102:105]
	v_mfma_f32_16x16x32_bf16 v[126:129], v[138:141], v[156:159], v[126:129]
	v_mfma_f32_16x16x32_bf16 v[122:125], v[148:151], v[156:159], v[122:125]
	v_mfma_f32_16x16x32_bf16 v[118:121], v[138:141], v[164:167], v[118:121]
	v_mfma_f32_16x16x32_bf16 v[114:117], v[148:151], v[164:167], v[114:117]
	v_mfma_f32_16x16x32_bf16 v[110:113], v[138:141], v[172:175], v[110:113]
	v_mfma_f32_16x16x32_bf16 v[106:109], v[148:151], v[172:175], v[106:109]
	v_mfma_f32_16x16x32_bf16 v[102:105], v[138:141], v[180:183], v[102:105]
	v_mfma_f32_16x16x32_bf16 v[98:101], v[144:147], v[176:179], v[98:101]
	v_mfma_f32_16x16x32_bf16 v[98:101], v[148:151], v[180:183], v[98:101]
	s_setprio 0
	v_add_u32_e32 v192, 0x14000, v143
	s_barrier
	ds_read_b128 v[130:133], v192
	ds_read_b128 v[184:187], v192 offset:1024
	ds_read_b128 v[188:191], v192 offset:2048
	ds_read_b128 v[192:195], v192 offset:3072
	s_barrier
	s_waitcnt lgkmcnt(0)
	s_setprio 1
	s_waitcnt lgkmcnt(0)
	v_mfma_f32_16x16x32_bf16 v[94:97], v[130:133], v[152:155], v[94:97]
	v_mfma_f32_16x16x32_bf16 v[90:93], v[188:191], v[152:155], v[90:93]
	v_mfma_f32_16x16x32_bf16 v[82:85], v[188:191], v[160:163], v[82:85]
	v_mfma_f32_16x16x32_bf16 v[70:73], v[188:191], v[168:171], v[70:73]
	v_mfma_f32_16x16x32_bf16 v[66:69], v[130:133], v[176:179], v[66:69]
	v_mfma_f32_16x16x32_bf16 v[94:97], v[184:187], v[156:159], v[94:97]
	v_mfma_f32_16x16x32_bf16 v[90:93], v[192:195], v[156:159], v[90:93]
	v_mfma_f32_16x16x32_bf16 v[86:89], v[130:133], v[160:163], v[86:89]
	v_mfma_f32_16x16x32_bf16 v[82:85], v[192:195], v[164:167], v[82:85]
	v_mfma_f32_16x16x32_bf16 v[78:81], v[130:133], v[168:171], v[78:81]
	v_mfma_f32_16x16x32_bf16 v[152:155], v[192:195], v[172:175], v[70:73]
	v_mfma_f32_16x16x32_bf16 v[156:159], v[184:187], v[180:183], v[66:69]
	v_mfma_f32_16x16x32_bf16 v[62:65], v[188:191], v[176:179], v[62:65]
	v_mfma_f32_16x16x32_bf16 v[86:89], v[184:187], v[164:167], v[86:89]
	v_mfma_f32_16x16x32_bf16 v[78:81], v[184:187], v[172:175], v[78:81]
	v_mfma_f32_16x16x32_bf16 v[160:163], v[192:195], v[180:183], v[62:65]
	s_setprio 0
	s_barrier
	s_nop 2
	ds_read_b128 v[62:65], v142 offset:16384
	ds_read_b128 v[66:69], v142 offset:17408
	ds_read_b128 v[70:73], v142 offset:18432
	ds_read_b128 v[164:167], v142 offset:19456
	ds_read_b128 v[168:171], v142 offset:20480
	ds_read_b128 v[172:175], v142 offset:21504
	ds_read_b128 v[176:179], v142 offset:22528
	ds_read_b128 v[180:183], v142 offset:23552
	s_waitcnt vmcnt(4)
	s_barrier
	s_waitcnt lgkmcnt(0)
	s_setprio 1
	s_waitcnt lgkmcnt(0)
	v_mfma_f32_16x16x32_bf16 v[58:61], v[134:137], v[62:65], v[58:61]
	v_mfma_f32_16x16x32_bf16 v[50:53], v[134:137], v[70:73], v[50:53]
	v_mfma_f32_16x16x32_bf16 v[42:45], v[134:137], v[168:171], v[42:45]
	v_mfma_f32_16x16x32_bf16 v[34:37], v[134:137], v[176:179], v[34:37]
	v_mfma_f32_16x16x32_bf16 v[30:33], v[144:147], v[176:179], v[30:33]
	v_mfma_f32_16x16x32_bf16 v[202:205], v[138:141], v[66:69], v[58:61]
	v_mfma_f32_16x16x32_bf16 v[54:57], v[144:147], v[62:65], v[54:57]
	v_mfma_f32_16x16x32_bf16 v[50:53], v[138:141], v[164:167], v[50:53]
	v_mfma_f32_16x16x32_bf16 v[46:49], v[144:147], v[70:73], v[46:49]
	v_mfma_f32_16x16x32_bf16 v[214:217], v[138:141], v[172:175], v[42:45]
	v_mfma_f32_16x16x32_bf16 v[38:41], v[144:147], v[168:171], v[38:41]
	v_mfma_f32_16x16x32_bf16 v[138:141], v[138:141], v[180:183], v[34:37]
	v_mfma_f32_16x16x32_bf16 v[144:147], v[148:151], v[180:183], v[30:33]
	v_mfma_f32_16x16x32_bf16 v[206:209], v[148:151], v[66:69], v[54:57]
	v_mfma_f32_16x16x32_bf16 v[210:213], v[148:151], v[164:167], v[46:49]
	v_mfma_f32_16x16x32_bf16 v[218:221], v[148:151], v[172:175], v[38:41]
	s_setprio 0
	s_setprio 1
	v_mfma_f32_16x16x32_bf16 v[26:29], v[130:133], v[62:65], v[26:29]
	v_mfma_f32_16x16x32_bf16 v[10:13], v[130:133], v[168:171], v[10:13]
	v_mfma_f32_16x16x32_bf16 v[6:9], v[188:191], v[168:171], v[6:9]
	v_mfma_f32_16x16x32_bf16 v[2:5], v[130:133], v[176:179], v[2:5]
	v_mfma_f32_16x16x32_bf16 v[148:151], v[184:187], v[66:69], v[26:29]
	v_mfma_f32_16x16x32_bf16 v[22:25], v[188:191], v[62:65], v[22:25]
	v_mfma_f32_16x16x32_bf16 v[18:21], v[130:133], v[70:73], v[18:21]
	v_mfma_f32_16x16x32_bf16 v[14:17], v[188:191], v[70:73], v[14:17]
	v_mfma_f32_16x16x32_bf16 v[238:241], v[184:187], v[172:175], v[10:13]
	v_mfma_f32_16x16x32_bf16 v[168:171], v[192:195], v[172:175], v[6:9]
	v_mfma_f32_16x16x32_bf16 v[172:175], v[184:187], v[180:183], v[2:5]
	v_mfma_f32_16x16x32_bf16 v[2:5], v[188:191], v[176:179], v[74:77]
	v_mfma_f32_16x16x32_bf16 v[230:233], v[192:195], v[66:69], v[22:25]
	v_mfma_f32_16x16x32_bf16 v[234:237], v[184:187], v[164:167], v[18:21]
	v_mfma_f32_16x16x32_bf16 v[164:167], v[192:195], v[164:167], v[14:17]
	v_mfma_f32_16x16x32_bf16 v[176:179], v[192:195], v[180:183], v[2:5]
	s_setprio 0
	v_add_u32_e32 v6, 0x18000, v143
	s_barrier
	s_nop 0
	ds_read_b128 v[2:5], v6
	ds_read_b128 v[72:75], v6 offset:1024
	ds_read_b128 v[180:183], v6 offset:2048
	ds_read_b128 v[184:187], v6 offset:3072
	ds_read_b128 v[6:9], v142 offset:32768
	ds_read_b128 v[14:17], v142 offset:33792
	ds_read_b128 v[18:21], v142 offset:34816
	ds_read_b128 v[28:31], v142 offset:35840
	ds_read_b128 v[188:191], v142 offset:36864
	ds_read_b128 v[192:195], v142 offset:37888
	ds_read_b128 v[242:245], v142 offset:38912
	ds_read_b128 v[246:249], v142 offset:39936
	s_waitcnt vmcnt(2)
	s_barrier
	s_waitcnt lgkmcnt(0)
	s_setprio 1
	s_waitcnt lgkmcnt(0)
	v_mfma_f32_16x16x32_bf16 v[10:13], v[2:5], v[6:9], v[126:129]
	v_mfma_f32_16x16x32_bf16 v[56:59], v[72:75], v[14:17], v[10:13]
	v_mfma_f32_16x16x32_bf16 v[10:13], v[180:183], v[6:9], v[122:125]
	v_mfma_f32_16x16x32_bf16 v[68:71], v[184:187], v[14:17], v[10:13]
	v_mfma_f32_16x16x32_bf16 v[10:13], v[2:5], v[18:21], v[118:121]
	v_mfma_f32_16x16x32_bf16 v[38:41], v[72:75], v[28:31], v[10:13]
	v_mfma_f32_16x16x32_bf16 v[10:13], v[180:183], v[18:21], v[114:117]
	v_mfma_f32_16x16x32_bf16 v[60:63], v[184:187], v[28:31], v[10:13]
	v_mfma_f32_16x16x32_bf16 v[10:13], v[2:5], v[188:191], v[110:113]
	v_mfma_f32_16x16x32_bf16 v[24:27], v[72:75], v[192:195], v[10:13]
	v_mfma_f32_16x16x32_bf16 v[10:13], v[180:183], v[188:191], v[106:109]
	v_mfma_f32_16x16x32_bf16 v[42:45], v[184:187], v[192:195], v[10:13]
	v_mfma_f32_16x16x32_bf16 v[10:13], v[2:5], v[242:245], v[102:105]
	v_mfma_f32_16x16x32_bf16 v[32:35], v[180:183], v[242:245], v[98:101]
	v_mfma_f32_16x16x32_bf16 v[10:13], v[72:75], v[246:249], v[10:13]
	v_mfma_f32_16x16x32_bf16 v[34:37], v[184:187], v[246:249], v[32:35]
	s_setprio 0
	v_add_u32_e32 v22, 0x1c000, v143
	s_barrier
	ds_read_b128 v[98:101], v22
	ds_read_b128 v[102:105], v22 offset:1024
	ds_read_b128 v[226:229], v22 offset:2048
	ds_read_b128 v[198:201], v22 offset:3072
	s_waitcnt vmcnt(0)
	s_barrier
	s_waitcnt lgkmcnt(0)
	s_setprio 1
	s_waitcnt lgkmcnt(0)
	v_mfma_f32_16x16x32_bf16 v[46:49], v[98:101], v[6:9], v[94:97]
	v_mfma_f32_16x16x32_bf16 v[6:9], v[226:229], v[6:9], v[90:93]
	v_mfma_f32_16x16x32_bf16 v[130:133], v[198:201], v[14:17], v[6:9]
	v_mfma_f32_16x16x32_bf16 v[6:9], v[98:101], v[18:21], v[86:89]
	v_mfma_f32_16x16x32_bf16 v[64:67], v[102:105], v[28:31], v[6:9]
	v_mfma_f32_16x16x32_bf16 v[6:9], v[226:229], v[18:21], v[82:85]
	v_mfma_f32_16x16x32_bf16 v[126:129], v[198:201], v[28:31], v[6:9]
	v_mfma_f32_16x16x32_bf16 v[6:9], v[98:101], v[188:191], v[78:81]
	v_mfma_f32_16x16x32_bf16 v[134:137], v[102:105], v[14:17], v[46:49]
	v_mfma_f32_16x16x32_bf16 v[46:49], v[102:105], v[192:195], v[6:9]
	v_mfma_f32_16x16x32_bf16 v[6:9], v[226:229], v[188:191], v[152:155]
	v_mfma_f32_16x16x32_bf16 v[122:125], v[198:201], v[192:195], v[6:9]
	v_mfma_f32_16x16x32_bf16 v[6:9], v[98:101], v[242:245], v[156:159]
	v_mfma_f32_16x16x32_bf16 v[16:19], v[102:105], v[246:249], v[6:9]
	v_mfma_f32_16x16x32_bf16 v[6:9], v[226:229], v[242:245], v[160:163]
	v_mfma_f32_16x16x32_bf16 v[118:121], v[198:201], v[246:249], v[6:9]
	s_setprio 0
	s_barrier
	ds_read_b128 v[76:79], v142 offset:49152
	ds_read_b128 v[86:89], v142 offset:50176
	ds_read_b128 v[106:109], v142 offset:51200
	ds_read_b128 v[110:113], v142 offset:52224
	ds_read_b128 v[158:161], v142 offset:53248
	ds_read_b128 v[188:191], v142 offset:54272
	ds_read_b128 v[192:195], v142 offset:55296
	ds_read_b128 v[242:245], v142 offset:56320
	s_barrier
	s_waitcnt lgkmcnt(0)
	s_setprio 1
	s_waitcnt lgkmcnt(0)
	v_mfma_f32_16x16x32_bf16 v[6:9], v[2:5], v[76:79], v[202:205]
	v_mfma_f32_16x16x32_bf16 v[154:157], v[72:75], v[86:89], v[6:9]
	v_mfma_f32_16x16x32_bf16 v[6:9], v[180:183], v[76:79], v[206:209]
	v_mfma_f32_16x16x32_bf16 v[30:33], v[184:187], v[86:89], v[6:9]
	v_mfma_f32_16x16x32_bf16 v[6:9], v[2:5], v[106:109], v[50:53]
	v_mfma_f32_16x16x32_bf16 v[92:95], v[72:75], v[110:113], v[6:9]
	v_mfma_f32_16x16x32_bf16 v[6:9], v[180:183], v[106:109], v[210:213]
	v_mfma_f32_16x16x32_bf16 v[20:23], v[184:187], v[110:113], v[6:9]
	v_mfma_f32_16x16x32_bf16 v[6:9], v[2:5], v[158:161], v[214:217]
	v_mfma_f32_16x16x32_bf16 v[2:5], v[2:5], v[192:195], v[138:141]
	v_mfma_f32_16x16x32_bf16 v[82:85], v[72:75], v[188:191], v[6:9]
	v_mfma_f32_16x16x32_bf16 v[6:9], v[180:183], v[158:161], v[218:221]
	v_mfma_f32_16x16x32_bf16 v[72:75], v[72:75], v[242:245], v[2:5]
	v_mfma_f32_16x16x32_bf16 v[2:5], v[180:183], v[192:195], v[144:147]
	v_mfma_f32_16x16x32_bf16 v[6:9], v[184:187], v[188:191], v[6:9]
	v_mfma_f32_16x16x32_bf16 v[2:5], v[184:187], v[242:245], v[2:5]
	s_setprio 0
	s_setprio 1
	v_mfma_f32_16x16x32_bf16 v[50:53], v[98:101], v[76:79], v[148:151]
	v_mfma_f32_16x16x32_bf16 v[150:153], v[102:105], v[86:89], v[50:53]
	v_mfma_f32_16x16x32_bf16 v[50:53], v[226:229], v[76:79], v[230:233]
	v_mfma_f32_16x16x32_bf16 v[114:117], v[198:201], v[86:89], v[50:53]
	v_mfma_f32_16x16x32_bf16 v[50:53], v[98:101], v[106:109], v[234:237]
	v_mfma_f32_16x16x32_bf16 v[146:149], v[102:105], v[110:113], v[50:53]
	v_mfma_f32_16x16x32_bf16 v[50:53], v[226:229], v[106:109], v[164:167]
	v_mfma_f32_16x16x32_bf16 v[110:113], v[198:201], v[110:113], v[50:53]
	v_mfma_f32_16x16x32_bf16 v[50:53], v[98:101], v[158:161], v[238:241]
	v_mfma_f32_16x16x32_bf16 v[142:145], v[102:105], v[188:191], v[50:53]
	v_mfma_f32_16x16x32_bf16 v[50:53], v[226:229], v[158:161], v[168:171]
	v_mfma_f32_16x16x32_bf16 v[106:109], v[198:201], v[188:191], v[50:53]
	v_mfma_f32_16x16x32_bf16 v[50:53], v[98:101], v[192:195], v[172:175]
	v_mfma_f32_16x16x32_bf16 v[138:141], v[102:105], v[242:245], v[50:53]
	v_mfma_f32_16x16x32_bf16 v[50:53], v[226:229], v[192:195], v[176:179]
	v_mfma_f32_16x16x32_bf16 v[102:105], v[198:201], v[242:245], v[50:53]
	s_setprio 0
	s_cmpk_lt_u32 s1, 0x100
	s_barrier
	s_cbranch_scc0 .LBB0_199
	s_barrier
